# GEMM MFMA blocks: mid-block s_setprio 0 / s_setprio 1 flip pairs deleted (16 sites); outer raise kept
# speedup vs baseline: 1.0062x; 1.0034x over previous
; #define PG8_STAGE(bufoff, gbase, voff) do { _Pragma("unroll") for (int _i = 0; _i < 2; ++_i) \
;         __builtin_amdgcn_global_load_lds((const unsigned*)((const char*)(gbase) + (voff)[_i]), (PG8_LAS unsigned*)(lds + (bufoff) + ldsw + _i * 8192), 16, 0, 0); } while (0)
; #define PG8_LDA(dst, b, h) do { _Pragma("unroll") for (int m = 0; m < 4; ++m) _Pragma("unroll") for (int k = 0; k < 2; ++k) dst[m][k] = *(const PG8_LAS bf16x8*)(lds + PG8_SA(b, h) + aoff + m * 2048 + k * 1024); } while (0)
; #define PG8_LDB(dst, b, h) do { _Pragma("unroll") for (int n = 0; n < 2; ++n) _Pragma("unroll") for (int k = 0; k < 2; ++k) dst[n][k] = *(const PG8_LAS bf16x8*)(lds + PG8_SB(b, h) + boff + n * 2048 + k * 1024); } while (0)
; #define PG8_MMA(ai, bj, At, Bt) do { __builtin_amdgcn_s_setprio(1); _Pragma("unroll") for (int m = 0; m < 4; ++m) _Pragma("unroll") for (int n = 0; n < 2; ++n) _Pragma("unroll") for (int k = 0; k < 2; ++k) \
;         acc[ai][bj][m][n] = __builtin_amdgcn_mfma_f32_16x16x32_bf16(Bt[n][k], At[m][k], acc[ai][bj][m][n], 0, 0, 0); __builtin_amdgcn_s_setprio(0); } while (0)
; #define PG8_WAIT_V(n) asm volatile("s_waitcnt vmcnt(" #n ")" ::: "memory")
; #define PG8_WAIT_L(n) asm volatile("s_waitcnt lgkmcnt(" #n ")" ::: "memory")
; #define PG8_BAR __builtin_amdgcn_s_barrier()
; #define PG8_SCHED __builtin_amdgcn_sched_barrier(0)
; template <class Epi, class Sched, bool ALIGN_EPI = false, bool SP2 = false>
; __device__ __forceinline__ void gemm_phase(PG8_LAS unsigned char* lds, const Gemm g, const Sched& S, const Epi& E) {
;     ...
;             const char* a1 = cA + (size_t)(t + 1) * kstep;
;             const char* a2 = last ? nA : cA + (size_t)(t + 2) * kstep; const char* b2 = last ? nB : cB + (size_t)(t + 2) * kstep;
;             const char* a3 = a2 + kstep; const char* b3 = b2 + kstep;
;             if (last && has_next) S.a_ready(nxt);
;             if constexpr (SP2) {
;             PG8_LDB(B0, 0, 0); PG8_LDB(B1, 0, 1); PG8_SCHED; PG8_LDA(At, 0, 0); PG8_STAGE(PG8_SA(1, 1), a1 + hstep, voffA);
;             PG8_WAIT_V(8); PG8_WAIT_L(0); PG8_BAR; PG8_MMA(0, 0, At, B0); PG8_MMA(0, 1, At, B1); PG8_BAR; PG8_SCHED;
;             PG8_LDA(At, 0, 1); PG8_STAGE(PG8_SB(0, 0), b2, voffB); PG8_STAGE(PG8_SB(0, 1), b2 + hstep, voffB); PG8_STAGE(PG8_SA(0, 0), a2, voffA);
.LBB0_97:
	s_add_u32 s24, s22, 0xfffc0080
	s_addc_u32 s25, s23, -1
	s_add_i32 s52, 0, 0x10000
	s_cmp_eq_u32 vcc_lo, 12
	s_cselect_b32 s27, s17, s25
	s_cselect_b32 s26, s44, s24
	s_cselect_b32 s25, s15, s47
	s_cselect_b32 s24, s45, s46
	s_add_i32 s53, 0, 0x14000
	v_add_u32_e32 v152, s52, v175
	v_add_u32_e32 v162, s53, v175
	ds_read_b128 v[0:3], v152
	ds_read_b128 v[4:7], v152 offset:1024
	ds_read_b128 v[148:151], v152 offset:2048
	ds_read_b128 v[152:155], v152 offset:3072
	ds_read_b128 v[156:159], v162
	ds_read_b128 v[182:185], v162 offset:1024
	ds_read_b128 v[186:189], v162 offset:2048
	ds_read_b128 v[190:193], v162 offset:3072
	v_lshl_add_u64 v[176:177], s[22:23], 0, v[144:145]
	s_add_i32 m0, s65, 0xc000
	ds_read_b128 v[194:197], v180
	ds_read_b128 v[198:201], v180 offset:1024
	ds_read_b128 v[202:205], v180 offset:2048
	ds_read_b128 v[206:209], v180 offset:3072
	ds_read_b128 v[210:213], v180 offset:4096
	ds_read_b128 v[214:217], v180 offset:5120
	ds_read_b128 v[218:221], v180 offset:6144
	ds_read_b128 v[232:235], v180 offset:7168
	global_load_lds_dwordx4 v[176:177], off
	v_lshl_add_u64 v[176:177], s[22:23], 0, v[146:147]
	s_add_i32 m0, s65, 0xe000
	s_nop 0
	global_load_lds_dwordx4 v[176:177], off
	s_waitcnt vmcnt(8)
	s_waitcnt lgkmcnt(0)
	s_barrier
	s_setprio 1
	s_waitcnt lgkmcnt(0)
	v_mfma_f32_16x16x32_bf16 v[132:135], v[0:3], v[194:197], v[132:135]
	v_mfma_f32_16x16x32_bf16 v[124:127], v[148:151], v[194:197], v[124:127]
	v_mfma_f32_16x16x32_bf16 v[116:119], v[0:3], v[202:205], v[116:119]
	v_mfma_f32_16x16x32_bf16 v[108:111], v[148:151], v[202:205], v[108:111]
	v_mfma_f32_16x16x32_bf16 v[100:103], v[0:3], v[210:213], v[100:103]
	v_mfma_f32_16x16x32_bf16 v[92:95], v[148:151], v[210:213], v[92:95]
	v_mfma_f32_16x16x32_bf16 v[84:87], v[0:3], v[218:221], v[84:87]
	v_mfma_f32_16x16x32_bf16 v[76:79], v[148:151], v[218:221], v[76:79]
	v_mfma_f32_16x16x32_bf16 v[132:135], v[4:7], v[198:201], v[132:135]
	v_mfma_f32_16x16x32_bf16 v[124:127], v[152:155], v[198:201], v[124:127]
	v_mfma_f32_16x16x32_bf16 v[116:119], v[4:7], v[206:209], v[116:119]
	v_mfma_f32_16x16x32_bf16 v[108:111], v[152:155], v[206:209], v[108:111]
	v_mfma_f32_16x16x32_bf16 v[100:103], v[4:7], v[214:217], v[100:103]
	v_mfma_f32_16x16x32_bf16 v[92:95], v[152:155], v[214:217], v[92:95]
	v_mfma_f32_16x16x32_bf16 v[84:87], v[4:7], v[232:235], v[84:87]
	v_mfma_f32_16x16x32_bf16 v[76:79], v[152:155], v[232:235], v[76:79]
	v_mfma_f32_16x16x32_bf16 v[128:131], v[156:159], v[194:197], v[128:131]
	v_mfma_f32_16x16x32_bf16 v[120:123], v[186:189], v[194:197], v[120:123]
	v_mfma_f32_16x16x32_bf16 v[112:115], v[156:159], v[202:205], v[112:115]
	v_mfma_f32_16x16x32_bf16 v[104:107], v[186:189], v[202:205], v[104:107]
	v_mfma_f32_16x16x32_bf16 v[96:99], v[156:159], v[210:213], v[96:99]
	v_mfma_f32_16x16x32_bf16 v[88:91], v[186:189], v[210:213], v[88:91]
	v_mfma_f32_16x16x32_bf16 v[80:83], v[156:159], v[218:221], v[80:83]
	v_mfma_f32_16x16x32_bf16 v[72:75], v[186:189], v[218:221], v[72:75]
	v_mfma_f32_16x16x32_bf16 v[128:131], v[182:185], v[198:201], v[128:131]
	v_mfma_f32_16x16x32_bf16 v[120:123], v[190:193], v[198:201], v[120:123]
	v_mfma_f32_16x16x32_bf16 v[112:115], v[182:185], v[206:209], v[112:115]
	v_mfma_f32_16x16x32_bf16 v[104:107], v[190:193], v[206:209], v[104:107]
	v_mfma_f32_16x16x32_bf16 v[96:99], v[182:185], v[214:217], v[96:99]
	v_mfma_f32_16x16x32_bf16 v[88:91], v[190:193], v[214:217], v[88:91]
	v_mfma_f32_16x16x32_bf16 v[80:83], v[182:185], v[232:235], v[80:83]
	v_mfma_f32_16x16x32_bf16 v[72:75], v[190:193], v[232:235], v[72:75]
	s_setprio 0
	s_barrier
	s_add_i32 s52, s52, s29
	v_lshl_add_u64 v[176:177], s[24:25], 0, v[160:161]
	s_mov_b32 m0, s52
	ds_read_b128 v[194:197], v180 offset:16384
	ds_read_b128 v[198:201], v180 offset:17408
	ds_read_b128 v[202:205], v180 offset:18432
	ds_read_b128 v[206:209], v180 offset:19456
	ds_read_b128 v[210:213], v180 offset:20480
	ds_read_b128 v[214:217], v180 offset:21504
	ds_read_b128 v[218:221], v180 offset:22528
	ds_read_b128 v[232:235], v180 offset:23552
	global_load_lds_dwordx4 v[176:177], off
	s_add_i32 m0, s52, 0x2000
	s_add_u32 s68, s24, 0x40000
	v_lshl_add_u64 v[222:223], s[24:25], 0, v[136:137]
	s_addc_u32 s69, s25, 0
	s_add_i32 s52, s53, s29
	global_load_lds_dwordx4 v[222:223], off
	v_lshl_add_u64 v[236:237], s[68:69], 0, v[160:161]
	s_mov_b32 m0, s52
	v_lshl_add_u64 v[238:239], s[26:27], 0, v[138:139]
	global_load_lds_dwordx4 v[236:237], off
	v_lshl_add_u64 v[236:237], s[68:69], 0, v[136:137]
	s_add_i32 m0, s52, 0x2000
	s_nop 0
	global_load_lds_dwordx4 v[236:237], off
	v_lshl_add_u64 v[236:237], s[26:27], 0, v[140:141]
	s_mov_b32 m0, s65
	s_nop 0
	global_load_lds_dwordx4 v[236:237], off
	s_mov_b32 m0, s76
	s_nop 0
	global_load_lds_dwordx4 v[238:239], off
	s_waitcnt vmcnt(8)
	s_waitcnt lgkmcnt(0)
	s_barrier
; #define PG8_STAGE(bufoff, gbase, voff) do { _Pragma("unroll") for (int _i = 0; _i < 2; ++_i) \
;         __builtin_amdgcn_global_load_lds((const unsigned*)((const char*)(gbase) + (voff)[_i]), (PG8_LAS unsigned*)(lds + (bufoff) + ldsw + _i * 8192), 16, 0, 0); } while (0)
; #define PG8_LDA(dst, b, h) do { _Pragma("unroll") for (int m = 0; m < 4; ++m) _Pragma("unroll") for (int k = 0; k < 2; ++k) dst[m][k] = *(const PG8_LAS bf16x8*)(lds + PG8_SA(b, h) + aoff + m * 2048 + k * 1024); } while (0)
; #define PG8_LDB(dst, b, h) do { _Pragma("unroll") for (int n = 0; n < 2; ++n) _Pragma("unroll") for (int k = 0; k < 2; ++k) dst[n][k] = *(const PG8_LAS bf16x8*)(lds + PG8_SB(b, h) + boff + n * 2048 + k * 1024); } while (0)
; #define PG8_MMA(ai, bj, At, Bt) do { __builtin_amdgcn_s_setprio(1); _Pragma("unroll") for (int m = 0; m < 4; ++m) _Pragma("unroll") for (int n = 0; n < 2; ++n) _Pragma("unroll") for (int k = 0; k < 2; ++k) \
;         acc[ai][bj][m][n] = __builtin_amdgcn_mfma_f32_16x16x32_bf16(Bt[n][k], At[m][k], acc[ai][bj][m][n], 0, 0, 0); __builtin_amdgcn_s_setprio(0); } while (0)
; #define PG8_WAIT_V(n) asm volatile("s_waitcnt vmcnt(" #n ")" ::: "memory")
; #define PG8_WAIT_L(n) asm volatile("s_waitcnt lgkmcnt(" #n ")" ::: "memory")
; #define PG8_BAR __builtin_amdgcn_s_barrier()
; #define PG8_SCHED __builtin_amdgcn_sched_barrier(0)
; template <class Epi, class Sched, bool ALIGN_EPI = false, bool SP2 = false>
; __device__ __forceinline__ void gemm_phase(PG8_LAS unsigned char* lds, const Gemm g, const Sched& S, const Epi& E) {
;     ...
;             PG8_WAIT_V(8); PG8_WAIT_L(0); PG8_BAR; PG8_MMA(1, 0, At, B0); PG8_MMA(1, 1, At, B1); PG8_BAR; PG8_SCHED;
;             PG8_LDB(B0, 1, 0); PG8_LDB(B1, 1, 1); PG8_SCHED; PG8_LDA(At, 1, 0); PG8_STAGE(PG8_SA(0, 1), a2 + hstep, voffA);
;             PG8_WAIT_V(8); PG8_WAIT_L(0); PG8_BAR; PG8_MMA(0, 0, At, B0); PG8_MMA(0, 1, At, B1); PG8_BAR; PG8_SCHED;
	s_setprio 1
	s_waitcnt lgkmcnt(0)
	v_mfma_f32_16x16x32_bf16 v[68:71], v[0:3], v[194:197], v[68:71]
	v_mfma_f32_16x16x32_bf16 v[60:63], v[148:151], v[194:197], v[60:63]
	v_mfma_f32_16x16x32_bf16 v[52:55], v[0:3], v[202:205], v[52:55]
	v_mfma_f32_16x16x32_bf16 v[44:47], v[148:151], v[202:205], v[44:47]
	v_mfma_f32_16x16x32_bf16 v[36:39], v[0:3], v[210:213], v[36:39]
	v_mfma_f32_16x16x32_bf16 v[28:31], v[148:151], v[210:213], v[28:31]
	v_mfma_f32_16x16x32_bf16 v[0:3], v[0:3], v[218:221], v[20:23]
	v_mfma_f32_16x16x32_bf16 v[68:71], v[4:7], v[198:201], v[68:71]
	v_mfma_f32_16x16x32_bf16 v[60:63], v[152:155], v[198:201], v[60:63]
	v_mfma_f32_16x16x32_bf16 v[52:55], v[4:7], v[206:209], v[52:55]
	v_mfma_f32_16x16x32_bf16 v[44:47], v[152:155], v[206:209], v[44:47]
	v_mfma_f32_16x16x32_bf16 v[36:39], v[4:7], v[214:217], v[36:39]
	v_mfma_f32_16x16x32_bf16 v[28:31], v[152:155], v[214:217], v[28:31]
	v_mfma_f32_16x16x32_bf16 v[0:3], v[4:7], v[232:235], v[0:3]
	v_mfma_f32_16x16x32_bf16 v[4:7], v[148:151], v[218:221], v[12:15]
	v_mfma_f32_16x16x32_bf16 v[4:7], v[152:155], v[232:235], v[4:7]
	v_mfma_f32_16x16x32_bf16 v[12:15], v[156:159], v[194:197], v[64:67]
	v_mfma_f32_16x16x32_bf16 v[64:67], v[182:185], v[198:201], v[12:15]
	v_mfma_f32_16x16x32_bf16 v[12:15], v[186:189], v[194:197], v[56:59]
	v_mfma_f32_16x16x32_bf16 v[56:59], v[190:193], v[198:201], v[12:15]
	v_mfma_f32_16x16x32_bf16 v[12:15], v[156:159], v[202:205], v[48:51]
	v_mfma_f32_16x16x32_bf16 v[48:51], v[182:185], v[206:209], v[12:15]
	v_mfma_f32_16x16x32_bf16 v[12:15], v[186:189], v[202:205], v[40:43]
	v_mfma_f32_16x16x32_bf16 v[40:43], v[190:193], v[206:209], v[12:15]
	v_mfma_f32_16x16x32_bf16 v[12:15], v[156:159], v[210:213], v[32:35]
	v_mfma_f32_16x16x32_bf16 v[32:35], v[182:185], v[214:217], v[12:15]
	v_mfma_f32_16x16x32_bf16 v[12:15], v[186:189], v[210:213], v[24:27]
	v_mfma_f32_16x16x32_bf16 v[24:27], v[190:193], v[214:217], v[12:15]
	v_mfma_f32_16x16x32_bf16 v[12:15], v[156:159], v[218:221], v[16:19]
	v_mfma_f32_16x16x32_bf16 v[8:11], v[186:189], v[218:221], v[8:11]
	v_mfma_f32_16x16x32_bf16 v[16:19], v[182:185], v[232:235], v[12:15]
	v_mfma_f32_16x16x32_bf16 v[8:11], v[190:193], v[232:235], v[8:11]
	s_setprio 0
	s_barrier
	s_add_i32 s52, 0, 0x18000
	s_add_i32 s53, 0, 0x1c000
	v_add_u32_e32 v152, s52, v175
	v_add_u32_e32 v162, s53, v175
	ds_read_b128 v[12:15], v152
	ds_read_b128 v[20:23], v152 offset:1024
	ds_read_b128 v[148:151], v152 offset:2048
	ds_read_b128 v[152:155], v152 offset:3072
	ds_read_b128 v[156:159], v162
	ds_read_b128 v[182:185], v162 offset:1024
	ds_read_b128 v[186:189], v162 offset:2048
	ds_read_b128 v[190:193], v162 offset:3072
	s_add_u32 s26, s26, 0x40000
	s_addc_u32 s27, s27, 0
	s_mov_b32 m0, s86
	v_lshl_add_u64 v[240:241], s[26:27], 0, v[140:141]
	ds_read_b128 v[194:197], v180 offset:32768
	ds_read_b128 v[198:201], v180 offset:33792
	ds_read_b128 v[202:205], v180 offset:34816
	ds_read_b128 v[206:209], v180 offset:35840
	ds_read_b128 v[210:213], v180 offset:36864
	ds_read_b128 v[214:217], v180 offset:37888
	ds_read_b128 v[218:221], v180 offset:38912
	ds_read_b128 v[232:235], v180 offset:39936
	global_load_lds_dwordx4 v[240:241], off
	v_lshl_add_u64 v[240:241], s[26:27], 0, v[138:139]
	s_mov_b32 m0, s87
	s_nop 0
	global_load_lds_dwordx4 v[240:241], off
	s_waitcnt vmcnt(8)
	s_waitcnt lgkmcnt(0)
	s_barrier
	s_setprio 1
	s_waitcnt lgkmcnt(0)
	v_mfma_f32_16x16x32_bf16 v[132:135], v[12:15], v[194:197], v[132:135]
	v_mfma_f32_16x16x32_bf16 v[124:127], v[148:151], v[194:197], v[124:127]
	v_mfma_f32_16x16x32_bf16 v[116:119], v[12:15], v[202:205], v[116:119]
	v_mfma_f32_16x16x32_bf16 v[108:111], v[148:151], v[202:205], v[108:111]
	v_mfma_f32_16x16x32_bf16 v[100:103], v[12:15], v[210:213], v[100:103]
	v_mfma_f32_16x16x32_bf16 v[92:95], v[148:151], v[210:213], v[92:95]
	v_mfma_f32_16x16x32_bf16 v[84:87], v[12:15], v[218:221], v[84:87]
	v_mfma_f32_16x16x32_bf16 v[76:79], v[148:151], v[218:221], v[76:79]
	v_mfma_f32_16x16x32_bf16 v[132:135], v[20:23], v[198:201], v[132:135]
	v_mfma_f32_16x16x32_bf16 v[124:127], v[152:155], v[198:201], v[124:127]
	v_mfma_f32_16x16x32_bf16 v[116:119], v[20:23], v[206:209], v[116:119]
	v_mfma_f32_16x16x32_bf16 v[108:111], v[152:155], v[206:209], v[108:111]
	v_mfma_f32_16x16x32_bf16 v[100:103], v[20:23], v[214:217], v[100:103]
	v_mfma_f32_16x16x32_bf16 v[92:95], v[152:155], v[214:217], v[92:95]
	v_mfma_f32_16x16x32_bf16 v[84:87], v[20:23], v[232:235], v[84:87]
	v_mfma_f32_16x16x32_bf16 v[76:79], v[152:155], v[232:235], v[76:79]
	v_mfma_f32_16x16x32_bf16 v[128:131], v[156:159], v[194:197], v[128:131]
	v_mfma_f32_16x16x32_bf16 v[120:123], v[186:189], v[194:197], v[120:123]
	v_mfma_f32_16x16x32_bf16 v[112:115], v[156:159], v[202:205], v[112:115]
	v_mfma_f32_16x16x32_bf16 v[104:107], v[186:189], v[202:205], v[104:107]
	v_mfma_f32_16x16x32_bf16 v[96:99], v[156:159], v[210:213], v[96:99]
	v_mfma_f32_16x16x32_bf16 v[88:91], v[186:189], v[210:213], v[88:91]
	v_mfma_f32_16x16x32_bf16 v[80:83], v[156:159], v[218:221], v[80:83]
	v_mfma_f32_16x16x32_bf16 v[72:75], v[186:189], v[218:221], v[72:75]
	v_mfma_f32_16x16x32_bf16 v[128:131], v[182:185], v[198:201], v[128:131]
	v_mfma_f32_16x16x32_bf16 v[120:123], v[190:193], v[198:201], v[120:123]
	v_mfma_f32_16x16x32_bf16 v[112:115], v[182:185], v[206:209], v[112:115]
	v_mfma_f32_16x16x32_bf16 v[104:107], v[190:193], v[206:209], v[104:107]
	v_mfma_f32_16x16x32_bf16 v[96:99], v[182:185], v[214:217], v[96:99]
	v_mfma_f32_16x16x32_bf16 v[88:91], v[190:193], v[214:217], v[88:91]
	v_mfma_f32_16x16x32_bf16 v[80:83], v[182:185], v[232:235], v[80:83]
	v_mfma_f32_16x16x32_bf16 v[72:75], v[190:193], v[232:235], v[72:75]
	s_setprio 0
	s_barrier
; #define PG8_STAGE(bufoff, gbase, voff) do { _Pragma("unroll") for (int _i = 0; _i < 2; ++_i) \
;         __builtin_amdgcn_global_load_lds((const unsigned*)((const char*)(gbase) + (voff)[_i]), (PG8_LAS unsigned*)(lds + (bufoff) + ldsw + _i * 8192), 16, 0, 0); } while (0)
; #define PG8_LDA(dst, b, h) do { _Pragma("unroll") for (int m = 0; m < 4; ++m) _Pragma("unroll") for (int k = 0; k < 2; ++k) dst[m][k] = *(const PG8_LAS bf16x8*)(lds + PG8_SA(b, h) + aoff + m * 2048 + k * 1024); } while (0)
; #define PG8_MMA(ai, bj, At, Bt) do { __builtin_amdgcn_s_setprio(1); _Pragma("unroll") for (int m = 0; m < 4; ++m) _Pragma("unroll") for (int n = 0; n < 2; ++n) _Pragma("unroll") for (int k = 0; k < 2; ++k) \
;         acc[ai][bj][m][n] = __builtin_amdgcn_mfma_f32_16x16x32_bf16(Bt[n][k], At[m][k], acc[ai][bj][m][n], 0, 0, 0); __builtin_amdgcn_s_setprio(0); } while (0)
; #define PG8_WAIT_V(n) asm volatile("s_waitcnt vmcnt(" #n ")" ::: "memory")
; #define PG8_WAIT_L(n) asm volatile("s_waitcnt lgkmcnt(" #n ")" ::: "memory")
; #define PG8_BAR __builtin_amdgcn_s_barrier()
; #define PG8_SCHED __builtin_amdgcn_sched_barrier(0)
; template <class Epi, class Sched, bool ALIGN_EPI = false, bool SP2 = false>
; __device__ __forceinline__ void gemm_phase(PG8_LAS unsigned char* lds, const Gemm g, const Sched& S, const Epi& E) {
;     ...
;             PG8_LDA(At, 1, 1); PG8_STAGE(PG8_SB(1, 0), b3, voffB); PG8_STAGE(PG8_SB(1, 1), b3 + hstep, voffB); PG8_STAGE(PG8_SA(1, 0), a3, voffA);
;             PG8_WAIT_V(8); PG8_WAIT_L(0); PG8_BAR; PG8_MMA(1, 0, At, B0); PG8_MMA(1, 1, At, B1); PG8_BAR; PG8_SCHED;
;     ...
;         if constexpr (ALIGN_EPI) { if (wr == 0) PG8_BAR; }
	s_add_i32 s26, s52, s29
	v_lshl_add_u64 v[176:177], v[176:177], 0, s[50:51]
	s_mov_b32 m0, s26
	ds_read_b128 v[194:197], v180 offset:49152
	ds_read_b128 v[198:201], v180 offset:50176
	ds_read_b128 v[202:205], v180 offset:51200
	ds_read_b128 v[206:209], v180 offset:52224
	ds_read_b128 v[210:213], v180 offset:53248
	ds_read_b128 v[214:217], v180 offset:54272
	ds_read_b128 v[218:221], v180 offset:55296
	ds_read_b128 v[232:235], v180 offset:56320
	global_load_lds_dwordx4 v[176:177], off
	s_add_i32 m0, s26, 0x2000
	s_add_u32 s24, s24, 0x40080
	v_lshl_add_u64 v[176:177], v[222:223], 0, s[50:51]
	s_addc_u32 s25, s25, 0
	s_add_i32 s26, s53, s29
	global_load_lds_dwordx4 v[176:177], off
	v_lshl_add_u64 v[176:177], s[24:25], 0, v[160:161]
	s_mov_b32 m0, s26
	s_nop 0
	global_load_lds_dwordx4 v[176:177], off
	v_lshl_add_u64 v[176:177], s[24:25], 0, v[136:137]
	s_add_i32 m0, s26, 0x2000
	s_nop 0
	global_load_lds_dwordx4 v[176:177], off
	v_lshl_add_u64 v[176:177], v[236:237], 0, s[50:51]
	s_mov_b32 m0, s0
	s_nop 0
	global_load_lds_dwordx4 v[176:177], off
	v_lshl_add_u64 v[176:177], v[238:239], 0, s[50:51]
	s_mov_b32 m0, s40
	s_nop 0
	global_load_lds_dwordx4 v[176:177], off
	s_waitcnt vmcnt(8)
	s_waitcnt lgkmcnt(0)
	s_barrier
	s_setprio 1
	s_waitcnt lgkmcnt(0)
	v_mfma_f32_16x16x32_bf16 v[68:71], v[12:15], v[194:197], v[68:71]
	v_mfma_f32_16x16x32_bf16 v[52:55], v[12:15], v[202:205], v[52:55]
	v_mfma_f32_16x16x32_bf16 v[36:39], v[12:15], v[210:213], v[36:39]
	v_mfma_f32_16x16x32_bf16 v[0:3], v[12:15], v[218:221], v[0:3]
	v_mfma_f32_16x16x32_bf16 v[68:71], v[20:23], v[198:201], v[68:71]
	v_mfma_f32_16x16x32_bf16 v[60:63], v[148:151], v[194:197], v[60:63]
	v_mfma_f32_16x16x32_bf16 v[52:55], v[20:23], v[206:209], v[52:55]
	v_mfma_f32_16x16x32_bf16 v[44:47], v[148:151], v[202:205], v[44:47]
	v_mfma_f32_16x16x32_bf16 v[36:39], v[20:23], v[214:217], v[36:39]
	v_mfma_f32_16x16x32_bf16 v[28:31], v[148:151], v[210:213], v[28:31]
	v_mfma_f32_16x16x32_bf16 v[20:23], v[20:23], v[232:235], v[0:3]
	v_mfma_f32_16x16x32_bf16 v[0:3], v[148:151], v[218:221], v[4:7]
	v_mfma_f32_16x16x32_bf16 v[60:63], v[152:155], v[198:201], v[60:63]
	v_mfma_f32_16x16x32_bf16 v[44:47], v[152:155], v[206:209], v[44:47]
	v_mfma_f32_16x16x32_bf16 v[28:31], v[152:155], v[214:217], v[28:31]
	v_mfma_f32_16x16x32_bf16 v[12:15], v[152:155], v[232:235], v[0:3]
	v_mfma_f32_16x16x32_bf16 v[0:3], v[156:159], v[194:197], v[64:67]
	v_mfma_f32_16x16x32_bf16 v[64:67], v[182:185], v[198:201], v[0:3]
	v_mfma_f32_16x16x32_bf16 v[0:3], v[186:189], v[194:197], v[56:59]
	v_mfma_f32_16x16x32_bf16 v[56:59], v[190:193], v[198:201], v[0:3]
	v_mfma_f32_16x16x32_bf16 v[0:3], v[156:159], v[202:205], v[48:51]
	v_mfma_f32_16x16x32_bf16 v[48:51], v[182:185], v[206:209], v[0:3]
	v_mfma_f32_16x16x32_bf16 v[0:3], v[186:189], v[202:205], v[40:43]
	v_mfma_f32_16x16x32_bf16 v[40:43], v[190:193], v[206:209], v[0:3]
	v_mfma_f32_16x16x32_bf16 v[0:3], v[156:159], v[210:213], v[32:35]
	v_mfma_f32_16x16x32_bf16 v[32:35], v[182:185], v[214:217], v[0:3]
	v_mfma_f32_16x16x32_bf16 v[0:3], v[186:189], v[210:213], v[24:27]
	v_mfma_f32_16x16x32_bf16 v[24:27], v[190:193], v[214:217], v[0:3]
	v_mfma_f32_16x16x32_bf16 v[0:3], v[156:159], v[218:221], v[16:19]
	v_mfma_f32_16x16x32_bf16 v[16:19], v[182:185], v[232:235], v[0:3]
	v_mfma_f32_16x16x32_bf16 v[0:3], v[186:189], v[218:221], v[8:11]
	v_mfma_f32_16x16x32_bf16 v[8:11], v[190:193], v[232:235], v[0:3]
	s_setprio 0
	s_barrier
	s_add_i32 vcc_lo, vcc_lo, 2
	s_add_u32 s22, s22, 0x100
	s_addc_u32 s23, s23, 0
	s_add_u32 s46, s46, 0x100
	s_addc_u32 s47, s47, 0
	s_cmp_gt_u32 vcc_lo, 13
	s_cbranch_scc0 .LBB0_97
	s_and_b64 vcc, exec, s[12:13]
	s_cbranch_vccz .LBB0_100
	s_barrier

; #define PG8_STAGE(bufoff, gbase, voff) do { _Pragma("unroll") for (int _i = 0; _i < 2; ++_i) \
;         __builtin_amdgcn_global_load_lds((const unsigned*)((const char*)(gbase) + (voff)[_i]), (PG8_LAS unsigned*)(lds + (bufoff) + ldsw + _i * 8192), 16, 0, 0); } while (0)
; #define PG8_LDA(dst, b, h) do { _Pragma("unroll") for (int m = 0; m < 4; ++m) _Pragma("unroll") for (int k = 0; k < 2; ++k) dst[m][k] = *(const PG8_LAS bf16x8*)(lds + PG8_SA(b, h) + aoff + m * 2048 + k * 1024); } while (0)
; #define PG8_LDB(dst, b, h) do { _Pragma("unroll") for (int n = 0; n < 2; ++n) _Pragma("unroll") for (int k = 0; k < 2; ++k) dst[n][k] = *(const PG8_LAS bf16x8*)(lds + PG8_SB(b, h) + boff + n * 2048 + k * 1024); } while (0)
; #define PG8_MMA(ai, bj, At, Bt) do { __builtin_amdgcn_s_setprio(1); _Pragma("unroll") for (int m = 0; m < 4; ++m) _Pragma("unroll") for (int n = 0; n < 2; ++n) _Pragma("unroll") for (int k = 0; k < 2; ++k) \
;         acc[ai][bj][m][n] = __builtin_amdgcn_mfma_f32_16x16x32_bf16(Bt[n][k], At[m][k], acc[ai][bj][m][n], 0, 0, 0); __builtin_amdgcn_s_setprio(0); } while (0)
; #define PG8_WAIT_V(n) asm volatile("s_waitcnt vmcnt(" #n ")" ::: "memory")
; #define PG8_WAIT_L(n) asm volatile("s_waitcnt lgkmcnt(" #n ")" ::: "memory")
; #define PG8_BAR __builtin_amdgcn_s_barrier()
; #define PG8_SCHED __builtin_amdgcn_sched_barrier(0)
; template <class Epi, class Sched, bool ALIGN_EPI = false, bool SP2 = false>
; __device__ __forceinline__ void gemm_phase(PG8_LAS unsigned char* lds, const Gemm g, const Sched& S, const Epi& E) {
;     ...
;             const char* a1 = cA + (size_t)(t + 1) * kstep;
;             const char* a2 = last ? nA : cA + (size_t)(t + 2) * kstep; const char* b2 = last ? nB : cB + (size_t)(t + 2) * kstep;
;             const char* a3 = a2 + kstep; const char* b3 = b2 + kstep;
;             if (last && has_next) S.a_ready(nxt);
;             if constexpr (SP2) {
;             PG8_LDB(B0, 0, 0); PG8_LDB(B1, 0, 1); PG8_SCHED; PG8_LDA(At, 0, 0); PG8_STAGE(PG8_SA(1, 1), a1 + hstep, voffA);
;             PG8_WAIT_V(8); PG8_WAIT_L(0); PG8_BAR; PG8_MMA(0, 0, At, B0); PG8_MMA(0, 1, At, B1); PG8_BAR; PG8_SCHED;
;             PG8_LDA(At, 0, 1); PG8_STAGE(PG8_SB(0, 0), b2, voffB); PG8_STAGE(PG8_SB(0, 1), b2 + hstep, voffB); PG8_STAGE(PG8_SA(0, 0), a2, voffA);
.LBB0_177:
	s_add_u32 s24, s22, 0x100
	s_addc_u32 s25, s23, 0
	s_add_i32 s52, 0, 0x10000
	s_cmp_eq_u32 s68, 40
	s_cselect_b32 s29, s9, s25
	s_cselect_b32 s28, s8, s24
	s_cselect_b32 s27, s21, vcc_hi
	s_cselect_b32 s26, s20, vcc_lo
	s_add_i32 s53, 0, 0x14000
	v_add_u32_e32 v140, s52, v175
	v_add_u32_e32 v162, s53, v175
	ds_read_b128 v[128:131], v140
	ds_read_b128 v[132:135], v140 offset:1024
	ds_read_b128 v[136:139], v140 offset:2048
	ds_read_b128 v[140:143], v140 offset:3072
	ds_read_b128 v[144:147], v162
	ds_read_b128 v[148:151], v162 offset:1024
	ds_read_b128 v[178:181], v162 offset:2048
	ds_read_b128 v[182:185], v162 offset:3072
	v_lshl_add_u64 v[218:219], s[22:23], 0, v[158:159]
	s_add_i32 m0, s41, 0xc000
	ds_read_b128 v[186:189], v233
	ds_read_b128 v[190:193], v233 offset:1024
	ds_read_b128 v[194:197], v233 offset:2048
	ds_read_b128 v[198:201], v233 offset:3072
	ds_read_b128 v[202:205], v233 offset:4096
	ds_read_b128 v[206:209], v233 offset:5120
	ds_read_b128 v[210:213], v233 offset:6144
	ds_read_b128 v[214:217], v233 offset:7168
	global_load_lds_dwordx4 v[218:219], off
	v_lshl_add_u64 v[218:219], s[22:23], 0, v[176:177]
	s_add_i32 m0, s41, 0xe000
	s_nop 0
	global_load_lds_dwordx4 v[218:219], off
	s_waitcnt vmcnt(8)
	s_waitcnt lgkmcnt(0)
	s_barrier
	s_setprio 1
	s_waitcnt lgkmcnt(0)
	v_mfma_f32_16x16x32_bf16 v[124:127], v[128:131], v[186:189], v[124:127]
	v_mfma_f32_16x16x32_bf16 v[120:123], v[136:139], v[186:189], v[120:123]
	v_mfma_f32_16x16x32_bf16 v[108:111], v[128:131], v[194:197], v[108:111]
	v_mfma_f32_16x16x32_bf16 v[104:107], v[136:139], v[194:197], v[104:107]
	v_mfma_f32_16x16x32_bf16 v[92:95], v[128:131], v[202:205], v[92:95]
	v_mfma_f32_16x16x32_bf16 v[88:91], v[136:139], v[202:205], v[88:91]
	v_mfma_f32_16x16x32_bf16 v[76:79], v[128:131], v[210:213], v[76:79]
	v_mfma_f32_16x16x32_bf16 v[72:75], v[136:139], v[210:213], v[72:75]
	v_mfma_f32_16x16x32_bf16 v[124:127], v[132:135], v[190:193], v[124:127]
	v_mfma_f32_16x16x32_bf16 v[120:123], v[140:143], v[190:193], v[120:123]
	v_mfma_f32_16x16x32_bf16 v[108:111], v[132:135], v[198:201], v[108:111]
	v_mfma_f32_16x16x32_bf16 v[104:107], v[140:143], v[198:201], v[104:107]
	v_mfma_f32_16x16x32_bf16 v[92:95], v[132:135], v[206:209], v[92:95]
	v_mfma_f32_16x16x32_bf16 v[88:91], v[140:143], v[206:209], v[88:91]
	v_mfma_f32_16x16x32_bf16 v[76:79], v[132:135], v[214:217], v[76:79]
	v_mfma_f32_16x16x32_bf16 v[72:75], v[140:143], v[214:217], v[72:75]
	v_mfma_f32_16x16x32_bf16 v[116:119], v[144:147], v[186:189], v[116:119]
	v_mfma_f32_16x16x32_bf16 v[112:115], v[178:181], v[186:189], v[112:115]
	v_mfma_f32_16x16x32_bf16 v[100:103], v[144:147], v[194:197], v[100:103]
	v_mfma_f32_16x16x32_bf16 v[96:99], v[178:181], v[194:197], v[96:99]
	v_mfma_f32_16x16x32_bf16 v[84:87], v[144:147], v[202:205], v[84:87]
	v_mfma_f32_16x16x32_bf16 v[80:83], v[178:181], v[202:205], v[80:83]
	v_mfma_f32_16x16x32_bf16 v[68:71], v[144:147], v[210:213], v[68:71]
	v_mfma_f32_16x16x32_bf16 v[64:67], v[178:181], v[210:213], v[64:67]
	v_mfma_f32_16x16x32_bf16 v[116:119], v[148:151], v[190:193], v[116:119]
	v_mfma_f32_16x16x32_bf16 v[112:115], v[182:185], v[190:193], v[112:115]
	v_mfma_f32_16x16x32_bf16 v[100:103], v[148:151], v[198:201], v[100:103]
	v_mfma_f32_16x16x32_bf16 v[96:99], v[182:185], v[198:201], v[96:99]
	v_mfma_f32_16x16x32_bf16 v[84:87], v[148:151], v[206:209], v[84:87]
	v_mfma_f32_16x16x32_bf16 v[80:83], v[182:185], v[206:209], v[80:83]
	v_mfma_f32_16x16x32_bf16 v[68:71], v[148:151], v[214:217], v[68:71]
	v_mfma_f32_16x16x32_bf16 v[64:67], v[182:185], v[214:217], v[64:67]
	s_setprio 0
	s_barrier
	s_add_i32 s22, s52, s40
	v_lshl_add_u64 v[218:219], s[26:27], 0, v[160:161]
	s_mov_b32 m0, s22
	ds_read_b128 v[186:189], v233 offset:16384
	ds_read_b128 v[190:193], v233 offset:17408
	ds_read_b128 v[194:197], v233 offset:18432
	ds_read_b128 v[198:201], v233 offset:19456
	ds_read_b128 v[202:205], v233 offset:20480
	ds_read_b128 v[206:209], v233 offset:21504
	ds_read_b128 v[210:213], v233 offset:22528
	ds_read_b128 v[214:217], v233 offset:23552
	global_load_lds_dwordx4 v[218:219], off
	s_add_i32 m0, s22, 0x2000
	s_add_u32 s22, s26, 0xb0000
	v_lshl_add_u64 v[220:221], s[26:27], 0, v[152:153]
	s_addc_u32 s23, s27, 0
	s_add_i32 s52, s53, s40
	global_load_lds_dwordx4 v[220:221], off
	v_lshl_add_u64 v[222:223], s[22:23], 0, v[160:161]
	s_mov_b32 m0, s52
	v_lshl_add_u64 v[234:235], s[28:29], 0, v[154:155]
	global_load_lds_dwordx4 v[222:223], off
	v_lshl_add_u64 v[222:223], s[22:23], 0, v[152:153]
	s_add_i32 m0, s52, 0x2000
	s_nop 0
	global_load_lds_dwordx4 v[222:223], off
	v_lshl_add_u64 v[222:223], s[28:29], 0, v[156:157]
	s_mov_b32 m0, s41
	s_nop 0
	global_load_lds_dwordx4 v[222:223], off
	s_mov_b32 m0, s42
	s_nop 0
	global_load_lds_dwordx4 v[234:235], off
	s_waitcnt vmcnt(8)
	s_waitcnt lgkmcnt(0)
	s_barrier
; #define PG8_STAGE(bufoff, gbase, voff) do { _Pragma("unroll") for (int _i = 0; _i < 2; ++_i) \
;         __builtin_amdgcn_global_load_lds((const unsigned*)((const char*)(gbase) + (voff)[_i]), (PG8_LAS unsigned*)(lds + (bufoff) + ldsw + _i * 8192), 16, 0, 0); } while (0)
; #define PG8_LDA(dst, b, h) do { _Pragma("unroll") for (int m = 0; m < 4; ++m) _Pragma("unroll") for (int k = 0; k < 2; ++k) dst[m][k] = *(const PG8_LAS bf16x8*)(lds + PG8_SA(b, h) + aoff + m * 2048 + k * 1024); } while (0)
; #define PG8_LDB(dst, b, h) do { _Pragma("unroll") for (int n = 0; n < 2; ++n) _Pragma("unroll") for (int k = 0; k < 2; ++k) dst[n][k] = *(const PG8_LAS bf16x8*)(lds + PG8_SB(b, h) + boff + n * 2048 + k * 1024); } while (0)
; #define PG8_MMA(ai, bj, At, Bt) do { __builtin_amdgcn_s_setprio(1); _Pragma("unroll") for (int m = 0; m < 4; ++m) _Pragma("unroll") for (int n = 0; n < 2; ++n) _Pragma("unroll") for (int k = 0; k < 2; ++k) \
;         acc[ai][bj][m][n] = __builtin_amdgcn_mfma_f32_16x16x32_bf16(Bt[n][k], At[m][k], acc[ai][bj][m][n], 0, 0, 0); __builtin_amdgcn_s_setprio(0); } while (0)
; #define PG8_WAIT_V(n) asm volatile("s_waitcnt vmcnt(" #n ")" ::: "memory")
; #define PG8_WAIT_L(n) asm volatile("s_waitcnt lgkmcnt(" #n ")" ::: "memory")
; #define PG8_BAR __builtin_amdgcn_s_barrier()
; #define PG8_SCHED __builtin_amdgcn_sched_barrier(0)
; template <class Epi, class Sched, bool ALIGN_EPI = false, bool SP2 = false>
; __device__ __forceinline__ void gemm_phase(PG8_LAS unsigned char* lds, const Gemm g, const Sched& S, const Epi& E) {
;     ...
;             PG8_WAIT_V(8); PG8_WAIT_L(0); PG8_BAR; PG8_MMA(1, 0, At, B0); PG8_MMA(1, 1, At, B1); PG8_BAR; PG8_SCHED;
;             PG8_LDB(B0, 1, 0); PG8_LDB(B1, 1, 1); PG8_SCHED; PG8_LDA(At, 1, 0); PG8_STAGE(PG8_SA(0, 1), a2 + hstep, voffA);
;             PG8_WAIT_V(8); PG8_WAIT_L(0); PG8_BAR; PG8_MMA(0, 0, At, B0); PG8_MMA(0, 1, At, B1); PG8_BAR; PG8_SCHED;
	s_setprio 1
	s_waitcnt lgkmcnt(0)
	v_mfma_f32_16x16x32_bf16 v[60:63], v[128:131], v[186:189], v[60:63]
	v_mfma_f32_16x16x32_bf16 v[56:59], v[136:139], v[186:189], v[56:59]
	v_mfma_f32_16x16x32_bf16 v[44:47], v[128:131], v[194:197], v[44:47]
	v_mfma_f32_16x16x32_bf16 v[40:43], v[136:139], v[194:197], v[40:43]
	v_mfma_f32_16x16x32_bf16 v[28:31], v[128:131], v[202:205], v[28:31]
	v_mfma_f32_16x16x32_bf16 v[24:27], v[136:139], v[202:205], v[24:27]
	v_mfma_f32_16x16x32_bf16 v[12:15], v[128:131], v[210:213], v[12:15]
	v_mfma_f32_16x16x32_bf16 v[8:11], v[136:139], v[210:213], v[8:11]
	v_mfma_f32_16x16x32_bf16 v[60:63], v[132:135], v[190:193], v[60:63]
	v_mfma_f32_16x16x32_bf16 v[56:59], v[140:143], v[190:193], v[56:59]
	v_mfma_f32_16x16x32_bf16 v[44:47], v[132:135], v[198:201], v[44:47]
	v_mfma_f32_16x16x32_bf16 v[40:43], v[140:143], v[198:201], v[40:43]
	v_mfma_f32_16x16x32_bf16 v[28:31], v[132:135], v[206:209], v[28:31]
	v_mfma_f32_16x16x32_bf16 v[24:27], v[140:143], v[206:209], v[24:27]
	v_mfma_f32_16x16x32_bf16 v[12:15], v[132:135], v[214:217], v[12:15]
	v_mfma_f32_16x16x32_bf16 v[8:11], v[140:143], v[214:217], v[8:11]
	v_mfma_f32_16x16x32_bf16 v[52:55], v[144:147], v[186:189], v[52:55]
	v_mfma_f32_16x16x32_bf16 v[48:51], v[178:181], v[186:189], v[48:51]
	v_mfma_f32_16x16x32_bf16 v[36:39], v[144:147], v[194:197], v[36:39]
	v_mfma_f32_16x16x32_bf16 v[32:35], v[178:181], v[194:197], v[32:35]
	v_mfma_f32_16x16x32_bf16 v[20:23], v[144:147], v[202:205], v[20:23]
	v_mfma_f32_16x16x32_bf16 v[16:19], v[178:181], v[202:205], v[16:19]
	v_mfma_f32_16x16x32_bf16 v[4:7], v[144:147], v[210:213], v[4:7]
	v_mfma_f32_16x16x32_bf16 v[0:3], v[178:181], v[210:213], v[0:3]
	v_mfma_f32_16x16x32_bf16 v[52:55], v[148:151], v[190:193], v[52:55]
	v_mfma_f32_16x16x32_bf16 v[48:51], v[182:185], v[190:193], v[48:51]
	v_mfma_f32_16x16x32_bf16 v[36:39], v[148:151], v[198:201], v[36:39]
	v_mfma_f32_16x16x32_bf16 v[32:35], v[182:185], v[198:201], v[32:35]
	v_mfma_f32_16x16x32_bf16 v[20:23], v[148:151], v[206:209], v[20:23]
	v_mfma_f32_16x16x32_bf16 v[16:19], v[182:185], v[206:209], v[16:19]
	v_mfma_f32_16x16x32_bf16 v[4:7], v[148:151], v[214:217], v[4:7]
	v_mfma_f32_16x16x32_bf16 v[0:3], v[182:185], v[214:217], v[0:3]
	s_setprio 0
	s_barrier
	s_add_i32 s52, 0, 0x18000
	s_add_i32 s53, 0, 0x1c000
	v_add_u32_e32 v140, s52, v175
	v_add_u32_e32 v162, s53, v175
	ds_read_b128 v[128:131], v140
	ds_read_b128 v[132:135], v140 offset:1024
	ds_read_b128 v[136:139], v140 offset:2048
	ds_read_b128 v[140:143], v140 offset:3072
	ds_read_b128 v[144:147], v162
	ds_read_b128 v[148:151], v162 offset:1024
	ds_read_b128 v[178:181], v162 offset:2048
	ds_read_b128 v[182:185], v162 offset:3072
	s_add_u32 s22, s28, 0xb0000
	s_addc_u32 s23, s29, 0
	s_mov_b32 m0, s43
	v_lshl_add_u64 v[236:237], s[22:23], 0, v[156:157]
	ds_read_b128 v[186:189], v233 offset:32768
	ds_read_b128 v[190:193], v233 offset:33792
	ds_read_b128 v[194:197], v233 offset:34816
	ds_read_b128 v[198:201], v233 offset:35840
	ds_read_b128 v[202:205], v233 offset:36864
	ds_read_b128 v[206:209], v233 offset:37888
	ds_read_b128 v[210:213], v233 offset:38912
	ds_read_b128 v[214:217], v233 offset:39936
	global_load_lds_dwordx4 v[236:237], off
	v_lshl_add_u64 v[236:237], s[22:23], 0, v[154:155]
	s_mov_b32 m0, s44
	s_nop 0
	global_load_lds_dwordx4 v[236:237], off
	s_waitcnt vmcnt(8)
	s_waitcnt lgkmcnt(0)
	s_barrier
	s_setprio 1
	s_waitcnt lgkmcnt(0)
	v_mfma_f32_16x16x32_bf16 v[124:127], v[128:131], v[186:189], v[124:127]
	v_mfma_f32_16x16x32_bf16 v[120:123], v[136:139], v[186:189], v[120:123]
	v_mfma_f32_16x16x32_bf16 v[108:111], v[128:131], v[194:197], v[108:111]
	v_mfma_f32_16x16x32_bf16 v[104:107], v[136:139], v[194:197], v[104:107]
	v_mfma_f32_16x16x32_bf16 v[92:95], v[128:131], v[202:205], v[92:95]
	v_mfma_f32_16x16x32_bf16 v[88:91], v[136:139], v[202:205], v[88:91]
	v_mfma_f32_16x16x32_bf16 v[76:79], v[128:131], v[210:213], v[76:79]
	v_mfma_f32_16x16x32_bf16 v[72:75], v[136:139], v[210:213], v[72:75]
	v_mfma_f32_16x16x32_bf16 v[124:127], v[132:135], v[190:193], v[124:127]
	v_mfma_f32_16x16x32_bf16 v[120:123], v[140:143], v[190:193], v[120:123]
	v_mfma_f32_16x16x32_bf16 v[108:111], v[132:135], v[198:201], v[108:111]
	v_mfma_f32_16x16x32_bf16 v[104:107], v[140:143], v[198:201], v[104:107]
	v_mfma_f32_16x16x32_bf16 v[92:95], v[132:135], v[206:209], v[92:95]
	v_mfma_f32_16x16x32_bf16 v[88:91], v[140:143], v[206:209], v[88:91]
	v_mfma_f32_16x16x32_bf16 v[76:79], v[132:135], v[214:217], v[76:79]
	v_mfma_f32_16x16x32_bf16 v[72:75], v[140:143], v[214:217], v[72:75]
	v_mfma_f32_16x16x32_bf16 v[116:119], v[144:147], v[186:189], v[116:119]
	v_mfma_f32_16x16x32_bf16 v[112:115], v[178:181], v[186:189], v[112:115]
	v_mfma_f32_16x16x32_bf16 v[100:103], v[144:147], v[194:197], v[100:103]
	v_mfma_f32_16x16x32_bf16 v[96:99], v[178:181], v[194:197], v[96:99]
	v_mfma_f32_16x16x32_bf16 v[84:87], v[144:147], v[202:205], v[84:87]
	v_mfma_f32_16x16x32_bf16 v[80:83], v[178:181], v[202:205], v[80:83]
	v_mfma_f32_16x16x32_bf16 v[68:71], v[144:147], v[210:213], v[68:71]
	v_mfma_f32_16x16x32_bf16 v[64:67], v[178:181], v[210:213], v[64:67]
	v_mfma_f32_16x16x32_bf16 v[116:119], v[148:151], v[190:193], v[116:119]
	v_mfma_f32_16x16x32_bf16 v[112:115], v[182:185], v[190:193], v[112:115]
	v_mfma_f32_16x16x32_bf16 v[100:103], v[148:151], v[198:201], v[100:103]
	v_mfma_f32_16x16x32_bf16 v[96:99], v[182:185], v[198:201], v[96:99]
	v_mfma_f32_16x16x32_bf16 v[84:87], v[148:151], v[206:209], v[84:87]
	v_mfma_f32_16x16x32_bf16 v[80:83], v[182:185], v[206:209], v[80:83]
	v_mfma_f32_16x16x32_bf16 v[68:71], v[148:151], v[214:217], v[68:71]
	v_mfma_f32_16x16x32_bf16 v[64:67], v[182:185], v[214:217], v[64:67]
	s_setprio 0
	s_barrier
; #define PG8_STAGE(bufoff, gbase, voff) do { _Pragma("unroll") for (int _i = 0; _i < 2; ++_i) \
;         __builtin_amdgcn_global_load_lds((const unsigned*)((const char*)(gbase) + (voff)[_i]), (PG8_LAS unsigned*)(lds + (bufoff) + ldsw + _i * 8192), 16, 0, 0); } while (0)
; #define PG8_LDA(dst, b, h) do { _Pragma("unroll") for (int m = 0; m < 4; ++m) _Pragma("unroll") for (int k = 0; k < 2; ++k) dst[m][k] = *(const PG8_LAS bf16x8*)(lds + PG8_SA(b, h) + aoff + m * 2048 + k * 1024); } while (0)
; #define PG8_MMA(ai, bj, At, Bt) do { __builtin_amdgcn_s_setprio(1); _Pragma("unroll") for (int m = 0; m < 4; ++m) _Pragma("unroll") for (int n = 0; n < 2; ++n) _Pragma("unroll") for (int k = 0; k < 2; ++k) \
;         acc[ai][bj][m][n] = __builtin_amdgcn_mfma_f32_16x16x32_bf16(Bt[n][k], At[m][k], acc[ai][bj][m][n], 0, 0, 0); __builtin_amdgcn_s_setprio(0); } while (0)
; #define PG8_WAIT_V(n) asm volatile("s_waitcnt vmcnt(" #n ")" ::: "memory")
; #define PG8_WAIT_L(n) asm volatile("s_waitcnt lgkmcnt(" #n ")" ::: "memory")
; #define PG8_BAR __builtin_amdgcn_s_barrier()
; #define PG8_SCHED __builtin_amdgcn_sched_barrier(0)
; template <class Epi, class Sched, bool ALIGN_EPI = false, bool SP2 = false>
; __device__ __forceinline__ void gemm_phase(PG8_LAS unsigned char* lds, const Gemm g, const Sched& S, const Epi& E) {
;     ...
;             PG8_LDA(At, 1, 1); PG8_STAGE(PG8_SB(1, 0), b3, voffB); PG8_STAGE(PG8_SB(1, 1), b3 + hstep, voffB); PG8_STAGE(PG8_SA(1, 0), a3, voffA);
;             PG8_WAIT_V(8); PG8_WAIT_L(0); PG8_BAR; PG8_MMA(1, 0, At, B0); PG8_MMA(1, 1, At, B1); PG8_BAR; PG8_SCHED;
;     ...
;         if constexpr (ALIGN_EPI) { if (wr == 0) PG8_BAR; }
	s_add_i32 s22, s52, s40
	v_lshl_add_u64 v[218:219], v[218:219], 0, s[50:51]
	s_mov_b32 m0, s22
	ds_read_b128 v[186:189], v233 offset:49152
	ds_read_b128 v[190:193], v233 offset:50176
	ds_read_b128 v[194:197], v233 offset:51200
	ds_read_b128 v[198:201], v233 offset:52224
	ds_read_b128 v[202:205], v233 offset:53248
	ds_read_b128 v[206:209], v233 offset:54272
	ds_read_b128 v[210:213], v233 offset:55296
	ds_read_b128 v[214:217], v233 offset:56320
	global_load_lds_dwordx4 v[218:219], off
	s_add_i32 m0, s22, 0x2000
	s_add_u32 s22, s26, 0xb0080
	v_lshl_add_u64 v[218:219], v[220:221], 0, s[50:51]
	s_addc_u32 s23, s27, 0
	s_add_i32 s26, s53, s40
	global_load_lds_dwordx4 v[218:219], off
	v_lshl_add_u64 v[218:219], s[22:23], 0, v[160:161]
	s_mov_b32 m0, s26
	s_nop 0
	global_load_lds_dwordx4 v[218:219], off
	v_lshl_add_u64 v[218:219], s[22:23], 0, v[152:153]
	s_add_i32 m0, s26, 0x2000
	s_nop 0
	global_load_lds_dwordx4 v[218:219], off
	v_lshl_add_u64 v[218:219], v[222:223], 0, s[50:51]
	s_mov_b32 m0, s46
	s_nop 0
	global_load_lds_dwordx4 v[218:219], off
	v_lshl_add_u64 v[218:219], v[234:235], 0, s[50:51]
	s_mov_b32 m0, s47
	s_nop 0
	global_load_lds_dwordx4 v[218:219], off
	s_waitcnt vmcnt(8)
	s_waitcnt lgkmcnt(0)
	s_barrier
	s_setprio 1
	s_waitcnt lgkmcnt(0)
	v_mfma_f32_16x16x32_bf16 v[60:63], v[128:131], v[186:189], v[60:63]
	v_mfma_f32_16x16x32_bf16 v[56:59], v[136:139], v[186:189], v[56:59]
	v_mfma_f32_16x16x32_bf16 v[44:47], v[128:131], v[194:197], v[44:47]
	v_mfma_f32_16x16x32_bf16 v[40:43], v[136:139], v[194:197], v[40:43]
	v_mfma_f32_16x16x32_bf16 v[28:31], v[128:131], v[202:205], v[28:31]
	v_mfma_f32_16x16x32_bf16 v[24:27], v[136:139], v[202:205], v[24:27]
	v_mfma_f32_16x16x32_bf16 v[12:15], v[128:131], v[210:213], v[12:15]
	v_mfma_f32_16x16x32_bf16 v[8:11], v[136:139], v[210:213], v[8:11]
	v_mfma_f32_16x16x32_bf16 v[60:63], v[132:135], v[190:193], v[60:63]
	v_mfma_f32_16x16x32_bf16 v[56:59], v[140:143], v[190:193], v[56:59]
	v_mfma_f32_16x16x32_bf16 v[44:47], v[132:135], v[198:201], v[44:47]
	v_mfma_f32_16x16x32_bf16 v[40:43], v[140:143], v[198:201], v[40:43]
	v_mfma_f32_16x16x32_bf16 v[28:31], v[132:135], v[206:209], v[28:31]
	v_mfma_f32_16x16x32_bf16 v[24:27], v[140:143], v[206:209], v[24:27]
	v_mfma_f32_16x16x32_bf16 v[12:15], v[132:135], v[214:217], v[12:15]
	v_mfma_f32_16x16x32_bf16 v[8:11], v[140:143], v[214:217], v[8:11]
	v_mfma_f32_16x16x32_bf16 v[52:55], v[144:147], v[186:189], v[52:55]
	v_mfma_f32_16x16x32_bf16 v[48:51], v[178:181], v[186:189], v[48:51]
	v_mfma_f32_16x16x32_bf16 v[36:39], v[144:147], v[194:197], v[36:39]
	v_mfma_f32_16x16x32_bf16 v[32:35], v[178:181], v[194:197], v[32:35]
	v_mfma_f32_16x16x32_bf16 v[20:23], v[144:147], v[202:205], v[20:23]
	v_mfma_f32_16x16x32_bf16 v[16:19], v[178:181], v[202:205], v[16:19]
	v_mfma_f32_16x16x32_bf16 v[4:7], v[144:147], v[210:213], v[4:7]
	v_mfma_f32_16x16x32_bf16 v[0:3], v[178:181], v[210:213], v[0:3]
	v_mfma_f32_16x16x32_bf16 v[52:55], v[148:151], v[190:193], v[52:55]
	v_mfma_f32_16x16x32_bf16 v[48:51], v[182:185], v[190:193], v[48:51]
	v_mfma_f32_16x16x32_bf16 v[36:39], v[148:151], v[198:201], v[36:39]
	v_mfma_f32_16x16x32_bf16 v[32:35], v[182:185], v[198:201], v[32:35]
	v_mfma_f32_16x16x32_bf16 v[20:23], v[148:151], v[206:209], v[20:23]
	v_mfma_f32_16x16x32_bf16 v[16:19], v[182:185], v[206:209], v[16:19]
	v_mfma_f32_16x16x32_bf16 v[4:7], v[148:151], v[214:217], v[4:7]
	v_mfma_f32_16x16x32_bf16 v[0:3], v[182:185], v[214:217], v[0:3]
	s_setprio 0
	s_barrier
	s_add_i32 s68, s68, 2
	s_add_u32 vcc_lo, vcc_lo, 0x100
	s_addc_u32 vcc_hi, vcc_hi, 0
	s_cmp_gt_u32 s68, 41
	s_mov_b64 s[22:23], s[24:25]
	s_cbranch_scc0 .LBB0_177
	s_and_b64 vcc, exec, s[18:19]
	s_cbranch_vccz .LBB0_180
	s_barrier

; #define PG8_STAGE(bufoff, gbase, voff) do { _Pragma("unroll") for (int _i = 0; _i < 2; ++_i) \
;         __builtin_amdgcn_global_load_lds((const unsigned*)((const char*)(gbase) + (voff)[_i]), (PG8_LAS unsigned*)(lds + (bufoff) + ldsw + _i * 8192), 16, 0, 0); } while (0)
; #define PG8_LDA(dst, b, h) do { _Pragma("unroll") for (int m = 0; m < 4; ++m) _Pragma("unroll") for (int k = 0; k < 2; ++k) dst[m][k] = *(const PG8_LAS bf16x8*)(lds + PG8_SA(b, h) + aoff + m * 2048 + k * 1024); } while (0)
; #define PG8_LDB(dst, b, h) do { _Pragma("unroll") for (int n = 0; n < 2; ++n) _Pragma("unroll") for (int k = 0; k < 2; ++k) dst[n][k] = *(const PG8_LAS bf16x8*)(lds + PG8_SB(b, h) + boff + n * 2048 + k * 1024); } while (0)
; #define PG8_MMA(ai, bj, At, Bt) do { __builtin_amdgcn_s_setprio(1); _Pragma("unroll") for (int m = 0; m < 4; ++m) _Pragma("unroll") for (int n = 0; n < 2; ++n) _Pragma("unroll") for (int k = 0; k < 2; ++k) \
;         acc[ai][bj][m][n] = __builtin_amdgcn_mfma_f32_16x16x32_bf16(Bt[n][k], At[m][k], acc[ai][bj][m][n], 0, 0, 0); __builtin_amdgcn_s_setprio(0); } while (0)
; #define PG8_WAIT_V(n) asm volatile("s_waitcnt vmcnt(" #n ")" ::: "memory")
; #define PG8_WAIT_L(n) asm volatile("s_waitcnt lgkmcnt(" #n ")" ::: "memory")
; #define PG8_BAR __builtin_amdgcn_s_barrier()
; #define PG8_SCHED __builtin_amdgcn_sched_barrier(0)
; template <class Epi, class Sched, bool ALIGN_EPI = false, bool SP2 = false>
; __device__ __forceinline__ void gemm_phase(PG8_LAS unsigned char* lds, const Gemm g, const Sched& S, const Epi& E) {
;     ...
;             const char* a1 = cA + (size_t)(t + 1) * kstep;
;             const char* a2 = last ? nA : cA + (size_t)(t + 2) * kstep; const char* b2 = last ? nB : cB + (size_t)(t + 2) * kstep;
;             const char* a3 = a2 + kstep; const char* b3 = b2 + kstep;
;             if (last && has_next) S.a_ready(nxt);
;             if constexpr (SP2) {
;             PG8_LDB(B0, 0, 0); PG8_LDB(B1, 0, 1); PG8_SCHED; PG8_LDA(At, 0, 0); PG8_STAGE(PG8_SA(1, 1), a1 + hstep, voffA);
;             PG8_WAIT_V(8); PG8_WAIT_L(0); PG8_BAR; PG8_MMA(0, 0, At, B0); PG8_MMA(0, 1, At, B1); PG8_BAR; PG8_SCHED;
;             PG8_LDA(At, 0, 1); PG8_STAGE(PG8_SB(0, 0), b2, voffB); PG8_STAGE(PG8_SB(0, 1), b2 + hstep, voffB); PG8_STAGE(PG8_SA(0, 0), a2, voffA);
.LBB0_270:
	s_add_u32 s8, s6, 0xfffc0080
	s_addc_u32 s9, s7, -1
	s_add_i32 s52, 0, 0x10000
	s_cmp_eq_u32 s86, 12
	s_cselect_b32 s25, s19, s9
	s_cselect_b32 s24, s47, s8
	s_cselect_b32 s9, s17, s76
	s_cselect_b32 s8, s64, s65
	s_add_i32 s53, 0, 0x14000
	v_add_u32_e32 v140, s52, v175
	v_add_u32_e32 v156, s53, v175
	ds_read_b128 v[128:131], v140
	ds_read_b128 v[132:135], v140 offset:1024
	ds_read_b128 v[136:139], v140 offset:2048
	ds_read_b128 v[140:143], v140 offset:3072
	ds_read_b128 v[144:147], v156
	ds_read_b128 v[148:151], v156 offset:1024
	ds_read_b128 v[152:155], v156 offset:2048
	ds_read_b128 v[156:159], v156 offset:3072
	v_lshl_add_u64 v[162:163], s[6:7], 0, v[186:187]
	s_add_i32 m0, s34, 0xc000
	ds_read_b128 v[190:193], v214
	ds_read_b128 v[194:197], v214 offset:1024
	ds_read_b128 v[198:201], v214 offset:2048
	ds_read_b128 v[202:205], v214 offset:3072
	ds_read_b128 v[206:209], v214 offset:4096
	ds_read_b128 v[216:219], v214 offset:5120
	ds_read_b128 v[220:223], v214 offset:6144
	ds_read_b128 v[232:235], v214 offset:7168
	global_load_lds_dwordx4 v[162:163], off
	v_lshl_add_u64 v[162:163], s[6:7], 0, v[188:189]
	s_add_i32 m0, s34, 0xe000
	s_nop 0
	global_load_lds_dwordx4 v[162:163], off
	s_waitcnt vmcnt(8)
	s_waitcnt lgkmcnt(0)
	s_barrier
	s_setprio 1
	s_waitcnt lgkmcnt(0)
	v_mfma_f32_16x16x32_bf16 v[124:127], v[128:131], v[190:193], v[124:127]
	v_mfma_f32_16x16x32_bf16 v[120:123], v[136:139], v[190:193], v[120:123]
	v_mfma_f32_16x16x32_bf16 v[108:111], v[128:131], v[198:201], v[108:111]
	v_mfma_f32_16x16x32_bf16 v[104:107], v[136:139], v[198:201], v[104:107]
	v_mfma_f32_16x16x32_bf16 v[92:95], v[128:131], v[206:209], v[92:95]
	v_mfma_f32_16x16x32_bf16 v[88:91], v[136:139], v[206:209], v[88:91]
	v_mfma_f32_16x16x32_bf16 v[76:79], v[128:131], v[220:223], v[76:79]
	v_mfma_f32_16x16x32_bf16 v[72:75], v[136:139], v[220:223], v[72:75]
	v_mfma_f32_16x16x32_bf16 v[124:127], v[132:135], v[194:197], v[124:127]
	v_mfma_f32_16x16x32_bf16 v[120:123], v[140:143], v[194:197], v[120:123]
	v_mfma_f32_16x16x32_bf16 v[108:111], v[132:135], v[202:205], v[108:111]
	v_mfma_f32_16x16x32_bf16 v[104:107], v[140:143], v[202:205], v[104:107]
	v_mfma_f32_16x16x32_bf16 v[92:95], v[132:135], v[216:219], v[92:95]
	v_mfma_f32_16x16x32_bf16 v[88:91], v[140:143], v[216:219], v[88:91]
	v_mfma_f32_16x16x32_bf16 v[76:79], v[132:135], v[232:235], v[76:79]
	v_mfma_f32_16x16x32_bf16 v[72:75], v[140:143], v[232:235], v[72:75]
	v_mfma_f32_16x16x32_bf16 v[116:119], v[144:147], v[190:193], v[116:119]
	v_mfma_f32_16x16x32_bf16 v[112:115], v[152:155], v[190:193], v[112:115]
	v_mfma_f32_16x16x32_bf16 v[100:103], v[144:147], v[198:201], v[100:103]
	v_mfma_f32_16x16x32_bf16 v[96:99], v[152:155], v[198:201], v[96:99]
	v_mfma_f32_16x16x32_bf16 v[84:87], v[144:147], v[206:209], v[84:87]
	v_mfma_f32_16x16x32_bf16 v[80:83], v[152:155], v[206:209], v[80:83]
	v_mfma_f32_16x16x32_bf16 v[68:71], v[144:147], v[220:223], v[68:71]
	v_mfma_f32_16x16x32_bf16 v[64:67], v[152:155], v[220:223], v[64:67]
	v_mfma_f32_16x16x32_bf16 v[116:119], v[148:151], v[194:197], v[116:119]
	v_mfma_f32_16x16x32_bf16 v[112:115], v[156:159], v[194:197], v[112:115]
	v_mfma_f32_16x16x32_bf16 v[100:103], v[148:151], v[202:205], v[100:103]
	v_mfma_f32_16x16x32_bf16 v[96:99], v[156:159], v[202:205], v[96:99]
	v_mfma_f32_16x16x32_bf16 v[84:87], v[148:151], v[216:219], v[84:87]
	v_mfma_f32_16x16x32_bf16 v[80:83], v[156:159], v[216:219], v[80:83]
	v_mfma_f32_16x16x32_bf16 v[68:71], v[148:151], v[232:235], v[68:71]
	v_mfma_f32_16x16x32_bf16 v[64:67], v[156:159], v[232:235], v[64:67]
	s_setprio 0
	s_barrier
	s_add_i32 s52, s52, s26
	v_lshl_add_u64 v[162:163], s[8:9], 0, v[160:161]
	s_mov_b32 m0, s52
	ds_read_b128 v[190:193], v214 offset:16384
	ds_read_b128 v[194:197], v214 offset:17408
	ds_read_b128 v[198:201], v214 offset:18432
	ds_read_b128 v[202:205], v214 offset:19456
	ds_read_b128 v[206:209], v214 offset:20480
	ds_read_b128 v[216:219], v214 offset:21504
	ds_read_b128 v[220:223], v214 offset:22528
	ds_read_b128 v[232:235], v214 offset:23552
	global_load_lds_dwordx4 v[162:163], off
	s_add_i32 m0, s52, 0x2000
	s_add_u32 s68, s8, 0x40000
	v_lshl_add_u64 v[164:165], s[8:9], 0, v[176:177]
	s_addc_u32 s69, s9, 0
	s_add_i32 s52, s53, s26
	global_load_lds_dwordx4 v[164:165], off
	v_lshl_add_u64 v[210:211], s[68:69], 0, v[160:161]
	s_mov_b32 m0, s52
	v_lshl_add_u64 v[226:227], s[24:25], 0, v[178:179]
	global_load_lds_dwordx4 v[210:211], off
	v_lshl_add_u64 v[210:211], s[68:69], 0, v[176:177]
	s_add_i32 m0, s52, 0x2000
	s_nop 0
	global_load_lds_dwordx4 v[210:211], off
	v_lshl_add_u64 v[210:211], s[24:25], 0, v[180:181]
	s_mov_b32 m0, s34
	s_nop 0
	global_load_lds_dwordx4 v[210:211], off
	s_mov_b32 m0, s35
	s_nop 0
	global_load_lds_dwordx4 v[226:227], off
	s_waitcnt vmcnt(8)
	s_waitcnt lgkmcnt(0)
	s_barrier
; #define PG8_STAGE(bufoff, gbase, voff) do { _Pragma("unroll") for (int _i = 0; _i < 2; ++_i) \
;         __builtin_amdgcn_global_load_lds((const unsigned*)((const char*)(gbase) + (voff)[_i]), (PG8_LAS unsigned*)(lds + (bufoff) + ldsw + _i * 8192), 16, 0, 0); } while (0)
; #define PG8_LDA(dst, b, h) do { _Pragma("unroll") for (int m = 0; m < 4; ++m) _Pragma("unroll") for (int k = 0; k < 2; ++k) dst[m][k] = *(const PG8_LAS bf16x8*)(lds + PG8_SA(b, h) + aoff + m * 2048 + k * 1024); } while (0)
; #define PG8_LDB(dst, b, h) do { _Pragma("unroll") for (int n = 0; n < 2; ++n) _Pragma("unroll") for (int k = 0; k < 2; ++k) dst[n][k] = *(const PG8_LAS bf16x8*)(lds + PG8_SB(b, h) + boff + n * 2048 + k * 1024); } while (0)
; #define PG8_MMA(ai, bj, At, Bt) do { __builtin_amdgcn_s_setprio(1); _Pragma("unroll") for (int m = 0; m < 4; ++m) _Pragma("unroll") for (int n = 0; n < 2; ++n) _Pragma("unroll") for (int k = 0; k < 2; ++k) \
;         acc[ai][bj][m][n] = __builtin_amdgcn_mfma_f32_16x16x32_bf16(Bt[n][k], At[m][k], acc[ai][bj][m][n], 0, 0, 0); __builtin_amdgcn_s_setprio(0); } while (0)
; #define PG8_WAIT_V(n) asm volatile("s_waitcnt vmcnt(" #n ")" ::: "memory")
; #define PG8_WAIT_L(n) asm volatile("s_waitcnt lgkmcnt(" #n ")" ::: "memory")
; #define PG8_BAR __builtin_amdgcn_s_barrier()
; #define PG8_SCHED __builtin_amdgcn_sched_barrier(0)
; template <class Epi, class Sched, bool ALIGN_EPI = false, bool SP2 = false>
; __device__ __forceinline__ void gemm_phase(PG8_LAS unsigned char* lds, const Gemm g, const Sched& S, const Epi& E) {
;     ...
;             PG8_WAIT_V(8); PG8_WAIT_L(0); PG8_BAR; PG8_MMA(1, 0, At, B0); PG8_MMA(1, 1, At, B1); PG8_BAR; PG8_SCHED;
;             PG8_LDB(B0, 1, 0); PG8_LDB(B1, 1, 1); PG8_SCHED; PG8_LDA(At, 1, 0); PG8_STAGE(PG8_SA(0, 1), a2 + hstep, voffA);
;             PG8_WAIT_V(8); PG8_WAIT_L(0); PG8_BAR; PG8_MMA(0, 0, At, B0); PG8_MMA(0, 1, At, B1); PG8_BAR; PG8_SCHED;
	s_setprio 1
	s_waitcnt lgkmcnt(0)
	v_mfma_f32_16x16x32_bf16 v[60:63], v[128:131], v[190:193], v[60:63]
	v_mfma_f32_16x16x32_bf16 v[56:59], v[136:139], v[190:193], v[56:59]
	v_mfma_f32_16x16x32_bf16 v[44:47], v[128:131], v[198:201], v[44:47]
	v_mfma_f32_16x16x32_bf16 v[40:43], v[136:139], v[198:201], v[40:43]
	v_mfma_f32_16x16x32_bf16 v[28:31], v[128:131], v[206:209], v[28:31]
	v_mfma_f32_16x16x32_bf16 v[24:27], v[136:139], v[206:209], v[24:27]
	v_mfma_f32_16x16x32_bf16 v[12:15], v[128:131], v[220:223], v[12:15]
	v_mfma_f32_16x16x32_bf16 v[8:11], v[136:139], v[220:223], v[8:11]
	v_mfma_f32_16x16x32_bf16 v[60:63], v[132:135], v[194:197], v[60:63]
	v_mfma_f32_16x16x32_bf16 v[56:59], v[140:143], v[194:197], v[56:59]
	v_mfma_f32_16x16x32_bf16 v[44:47], v[132:135], v[202:205], v[44:47]
	v_mfma_f32_16x16x32_bf16 v[40:43], v[140:143], v[202:205], v[40:43]
	v_mfma_f32_16x16x32_bf16 v[28:31], v[132:135], v[216:219], v[28:31]
	v_mfma_f32_16x16x32_bf16 v[24:27], v[140:143], v[216:219], v[24:27]
	v_mfma_f32_16x16x32_bf16 v[12:15], v[132:135], v[232:235], v[12:15]
	v_mfma_f32_16x16x32_bf16 v[8:11], v[140:143], v[232:235], v[8:11]
	v_mfma_f32_16x16x32_bf16 v[52:55], v[144:147], v[190:193], v[52:55]
	v_mfma_f32_16x16x32_bf16 v[48:51], v[152:155], v[190:193], v[48:51]
	v_mfma_f32_16x16x32_bf16 v[36:39], v[144:147], v[198:201], v[36:39]
	v_mfma_f32_16x16x32_bf16 v[32:35], v[152:155], v[198:201], v[32:35]
	v_mfma_f32_16x16x32_bf16 v[20:23], v[144:147], v[206:209], v[20:23]
	v_mfma_f32_16x16x32_bf16 v[16:19], v[152:155], v[206:209], v[16:19]
	v_mfma_f32_16x16x32_bf16 v[4:7], v[144:147], v[220:223], v[4:7]
	v_mfma_f32_16x16x32_bf16 v[0:3], v[152:155], v[220:223], v[0:3]
	v_mfma_f32_16x16x32_bf16 v[52:55], v[148:151], v[194:197], v[52:55]
	v_mfma_f32_16x16x32_bf16 v[48:51], v[156:159], v[194:197], v[48:51]
	v_mfma_f32_16x16x32_bf16 v[36:39], v[148:151], v[202:205], v[36:39]
	v_mfma_f32_16x16x32_bf16 v[32:35], v[156:159], v[202:205], v[32:35]
	v_mfma_f32_16x16x32_bf16 v[20:23], v[148:151], v[216:219], v[20:23]
	v_mfma_f32_16x16x32_bf16 v[16:19], v[156:159], v[216:219], v[16:19]
	v_mfma_f32_16x16x32_bf16 v[4:7], v[148:151], v[232:235], v[4:7]
	v_mfma_f32_16x16x32_bf16 v[0:3], v[156:159], v[232:235], v[0:3]
	s_setprio 0
	s_barrier
	s_add_i32 s52, 0, 0x18000
	s_add_i32 s53, 0, 0x1c000
	v_add_u32_e32 v140, s52, v175
	v_add_u32_e32 v156, s53, v175
	ds_read_b128 v[128:131], v140
	ds_read_b128 v[132:135], v140 offset:1024
	ds_read_b128 v[136:139], v140 offset:2048
	ds_read_b128 v[140:143], v140 offset:3072
	ds_read_b128 v[144:147], v156
	ds_read_b128 v[148:151], v156 offset:1024
	ds_read_b128 v[152:155], v156 offset:2048
	ds_read_b128 v[156:159], v156 offset:3072
	s_add_u32 s24, s24, 0x40000
	s_addc_u32 s25, s25, 0
	s_mov_b32 m0, s40
	v_lshl_add_u64 v[230:231], s[24:25], 0, v[180:181]
	ds_read_b128 v[190:193], v214 offset:32768
	ds_read_b128 v[194:197], v214 offset:33792
	ds_read_b128 v[198:201], v214 offset:34816
	ds_read_b128 v[202:205], v214 offset:35840
	ds_read_b128 v[206:209], v214 offset:36864
	ds_read_b128 v[216:219], v214 offset:37888
	ds_read_b128 v[220:223], v214 offset:38912
	ds_read_b128 v[232:235], v214 offset:39936
	global_load_lds_dwordx4 v[230:231], off
	v_lshl_add_u64 v[230:231], s[24:25], 0, v[178:179]
	s_mov_b32 m0, s41
	s_nop 0
	global_load_lds_dwordx4 v[230:231], off
	s_waitcnt vmcnt(8)
	s_waitcnt lgkmcnt(0)
	s_barrier
	s_setprio 1
	s_waitcnt lgkmcnt(0)
	v_mfma_f32_16x16x32_bf16 v[124:127], v[128:131], v[190:193], v[124:127]
	v_mfma_f32_16x16x32_bf16 v[120:123], v[136:139], v[190:193], v[120:123]
	v_mfma_f32_16x16x32_bf16 v[108:111], v[128:131], v[198:201], v[108:111]
	v_mfma_f32_16x16x32_bf16 v[104:107], v[136:139], v[198:201], v[104:107]
	v_mfma_f32_16x16x32_bf16 v[92:95], v[128:131], v[206:209], v[92:95]
	v_mfma_f32_16x16x32_bf16 v[88:91], v[136:139], v[206:209], v[88:91]
	v_mfma_f32_16x16x32_bf16 v[76:79], v[128:131], v[220:223], v[76:79]
	v_mfma_f32_16x16x32_bf16 v[72:75], v[136:139], v[220:223], v[72:75]
	v_mfma_f32_16x16x32_bf16 v[124:127], v[132:135], v[194:197], v[124:127]
	v_mfma_f32_16x16x32_bf16 v[120:123], v[140:143], v[194:197], v[120:123]
	v_mfma_f32_16x16x32_bf16 v[108:111], v[132:135], v[202:205], v[108:111]
	v_mfma_f32_16x16x32_bf16 v[104:107], v[140:143], v[202:205], v[104:107]
	v_mfma_f32_16x16x32_bf16 v[92:95], v[132:135], v[216:219], v[92:95]
	v_mfma_f32_16x16x32_bf16 v[88:91], v[140:143], v[216:219], v[88:91]
	v_mfma_f32_16x16x32_bf16 v[76:79], v[132:135], v[232:235], v[76:79]
	v_mfma_f32_16x16x32_bf16 v[72:75], v[140:143], v[232:235], v[72:75]
	v_mfma_f32_16x16x32_bf16 v[116:119], v[144:147], v[190:193], v[116:119]
	v_mfma_f32_16x16x32_bf16 v[112:115], v[152:155], v[190:193], v[112:115]
	v_mfma_f32_16x16x32_bf16 v[100:103], v[144:147], v[198:201], v[100:103]
	v_mfma_f32_16x16x32_bf16 v[96:99], v[152:155], v[198:201], v[96:99]
	v_mfma_f32_16x16x32_bf16 v[84:87], v[144:147], v[206:209], v[84:87]
	v_mfma_f32_16x16x32_bf16 v[80:83], v[152:155], v[206:209], v[80:83]
	v_mfma_f32_16x16x32_bf16 v[68:71], v[144:147], v[220:223], v[68:71]
	v_mfma_f32_16x16x32_bf16 v[64:67], v[152:155], v[220:223], v[64:67]
	v_mfma_f32_16x16x32_bf16 v[116:119], v[148:151], v[194:197], v[116:119]
	v_mfma_f32_16x16x32_bf16 v[112:115], v[156:159], v[194:197], v[112:115]
	v_mfma_f32_16x16x32_bf16 v[100:103], v[148:151], v[202:205], v[100:103]
	v_mfma_f32_16x16x32_bf16 v[96:99], v[156:159], v[202:205], v[96:99]
	v_mfma_f32_16x16x32_bf16 v[84:87], v[148:151], v[216:219], v[84:87]
	v_mfma_f32_16x16x32_bf16 v[80:83], v[156:159], v[216:219], v[80:83]
	v_mfma_f32_16x16x32_bf16 v[68:71], v[148:151], v[232:235], v[68:71]
	v_mfma_f32_16x16x32_bf16 v[64:67], v[156:159], v[232:235], v[64:67]
	s_setprio 0
	s_barrier
; #define PG8_STAGE(bufoff, gbase, voff) do { _Pragma("unroll") for (int _i = 0; _i < 2; ++_i) \
;         __builtin_amdgcn_global_load_lds((const unsigned*)((const char*)(gbase) + (voff)[_i]), (PG8_LAS unsigned*)(lds + (bufoff) + ldsw + _i * 8192), 16, 0, 0); } while (0)
; #define PG8_LDA(dst, b, h) do { _Pragma("unroll") for (int m = 0; m < 4; ++m) _Pragma("unroll") for (int k = 0; k < 2; ++k) dst[m][k] = *(const PG8_LAS bf16x8*)(lds + PG8_SA(b, h) + aoff + m * 2048 + k * 1024); } while (0)
; #define PG8_MMA(ai, bj, At, Bt) do { __builtin_amdgcn_s_setprio(1); _Pragma("unroll") for (int m = 0; m < 4; ++m) _Pragma("unroll") for (int n = 0; n < 2; ++n) _Pragma("unroll") for (int k = 0; k < 2; ++k) \
;         acc[ai][bj][m][n] = __builtin_amdgcn_mfma_f32_16x16x32_bf16(Bt[n][k], At[m][k], acc[ai][bj][m][n], 0, 0, 0); __builtin_amdgcn_s_setprio(0); } while (0)
; #define PG8_WAIT_V(n) asm volatile("s_waitcnt vmcnt(" #n ")" ::: "memory")
; #define PG8_WAIT_L(n) asm volatile("s_waitcnt lgkmcnt(" #n ")" ::: "memory")
; #define PG8_BAR __builtin_amdgcn_s_barrier()
; #define PG8_SCHED __builtin_amdgcn_sched_barrier(0)
; template <class Epi, class Sched, bool ALIGN_EPI = false, bool SP2 = false>
; __device__ __forceinline__ void gemm_phase(PG8_LAS unsigned char* lds, const Gemm g, const Sched& S, const Epi& E) {
;     ...
;             PG8_LDA(At, 1, 1); PG8_STAGE(PG8_SB(1, 0), b3, voffB); PG8_STAGE(PG8_SB(1, 1), b3 + hstep, voffB); PG8_STAGE(PG8_SA(1, 0), a3, voffA);
;             PG8_WAIT_V(8); PG8_WAIT_L(0); PG8_BAR; PG8_MMA(1, 0, At, B0); PG8_MMA(1, 1, At, B1); PG8_BAR; PG8_SCHED;
;     ...
;         if constexpr (ALIGN_EPI) { if (wr == 0) PG8_BAR; }
	s_add_i32 s24, s52, s26
	v_lshl_add_u64 v[162:163], v[162:163], 0, s[50:51]
	s_mov_b32 m0, s24
	ds_read_b128 v[190:193], v214 offset:49152
	ds_read_b128 v[194:197], v214 offset:50176
	ds_read_b128 v[198:201], v214 offset:51200
	ds_read_b128 v[202:205], v214 offset:52224
	ds_read_b128 v[206:209], v214 offset:53248
	ds_read_b128 v[216:219], v214 offset:54272
	ds_read_b128 v[220:223], v214 offset:55296
	ds_read_b128 v[232:235], v214 offset:56320
	global_load_lds_dwordx4 v[162:163], off
	s_add_i32 m0, s24, 0x2000
	s_add_u32 s8, s8, 0x40080
	v_lshl_add_u64 v[162:163], v[164:165], 0, s[50:51]
	s_addc_u32 s9, s9, 0
	s_add_i32 s24, s53, s26
	global_load_lds_dwordx4 v[162:163], off
	v_lshl_add_u64 v[162:163], s[8:9], 0, v[160:161]
	s_mov_b32 m0, s24
	s_nop 0
	global_load_lds_dwordx4 v[162:163], off
	v_lshl_add_u64 v[162:163], s[8:9], 0, v[176:177]
	s_add_i32 m0, s24, 0x2000
	s_nop 0
	global_load_lds_dwordx4 v[162:163], off
	v_lshl_add_u64 v[162:163], v[210:211], 0, s[50:51]
	s_mov_b32 m0, s42
	s_nop 0
	global_load_lds_dwordx4 v[162:163], off
	v_lshl_add_u64 v[162:163], v[226:227], 0, s[50:51]
	s_mov_b32 m0, s43
	s_nop 0
	global_load_lds_dwordx4 v[162:163], off
	s_waitcnt vmcnt(8)
	s_waitcnt lgkmcnt(0)
	s_barrier
	s_setprio 1
	s_waitcnt lgkmcnt(0)
	v_mfma_f32_16x16x32_bf16 v[60:63], v[128:131], v[190:193], v[60:63]
	v_mfma_f32_16x16x32_bf16 v[56:59], v[136:139], v[190:193], v[56:59]
	v_mfma_f32_16x16x32_bf16 v[44:47], v[128:131], v[198:201], v[44:47]
	v_mfma_f32_16x16x32_bf16 v[40:43], v[136:139], v[198:201], v[40:43]
	v_mfma_f32_16x16x32_bf16 v[28:31], v[128:131], v[206:209], v[28:31]
	v_mfma_f32_16x16x32_bf16 v[24:27], v[136:139], v[206:209], v[24:27]
	v_mfma_f32_16x16x32_bf16 v[12:15], v[128:131], v[220:223], v[12:15]
	v_mfma_f32_16x16x32_bf16 v[8:11], v[136:139], v[220:223], v[8:11]
	v_mfma_f32_16x16x32_bf16 v[60:63], v[132:135], v[194:197], v[60:63]
	v_mfma_f32_16x16x32_bf16 v[56:59], v[140:143], v[194:197], v[56:59]
	v_mfma_f32_16x16x32_bf16 v[44:47], v[132:135], v[202:205], v[44:47]
	v_mfma_f32_16x16x32_bf16 v[40:43], v[140:143], v[202:205], v[40:43]
	v_mfma_f32_16x16x32_bf16 v[28:31], v[132:135], v[216:219], v[28:31]
	v_mfma_f32_16x16x32_bf16 v[24:27], v[140:143], v[216:219], v[24:27]
	v_mfma_f32_16x16x32_bf16 v[12:15], v[132:135], v[232:235], v[12:15]
	v_mfma_f32_16x16x32_bf16 v[8:11], v[140:143], v[232:235], v[8:11]
	v_mfma_f32_16x16x32_bf16 v[52:55], v[144:147], v[190:193], v[52:55]
	v_mfma_f32_16x16x32_bf16 v[48:51], v[152:155], v[190:193], v[48:51]
	v_mfma_f32_16x16x32_bf16 v[36:39], v[144:147], v[198:201], v[36:39]
	v_mfma_f32_16x16x32_bf16 v[32:35], v[152:155], v[198:201], v[32:35]
	v_mfma_f32_16x16x32_bf16 v[20:23], v[144:147], v[206:209], v[20:23]
	v_mfma_f32_16x16x32_bf16 v[16:19], v[152:155], v[206:209], v[16:19]
	v_mfma_f32_16x16x32_bf16 v[4:7], v[144:147], v[220:223], v[4:7]
	v_mfma_f32_16x16x32_bf16 v[0:3], v[152:155], v[220:223], v[0:3]
	v_mfma_f32_16x16x32_bf16 v[52:55], v[148:151], v[194:197], v[52:55]
	v_mfma_f32_16x16x32_bf16 v[48:51], v[156:159], v[194:197], v[48:51]
	v_mfma_f32_16x16x32_bf16 v[36:39], v[148:151], v[202:205], v[36:39]
	v_mfma_f32_16x16x32_bf16 v[32:35], v[156:159], v[202:205], v[32:35]
	v_mfma_f32_16x16x32_bf16 v[20:23], v[148:151], v[216:219], v[20:23]
	v_mfma_f32_16x16x32_bf16 v[16:19], v[156:159], v[216:219], v[16:19]
	v_mfma_f32_16x16x32_bf16 v[4:7], v[148:151], v[232:235], v[4:7]
	v_mfma_f32_16x16x32_bf16 v[0:3], v[156:159], v[232:235], v[0:3]
	s_setprio 0
	s_barrier
	s_add_i32 s86, s86, 2
	s_add_u32 s6, s6, 0x100
	s_addc_u32 s7, s7, 0
	s_add_u32 s65, s65, 0x100
	s_addc_u32 s76, s76, 0
	s_cmp_gt_u32 s86, 13
	s_cbranch_scc0 .LBB0_270
	s_and_b64 vcc, exec, s[14:15]
	s_cbranch_vccz .LBB0_273
	s_barrier

; #define PG8_STAGE(bufoff, gbase, voff) do { _Pragma("unroll") for (int _i = 0; _i < 2; ++_i) \
;         __builtin_amdgcn_global_load_lds((const unsigned*)((const char*)(gbase) + (voff)[_i]), (PG8_LAS unsigned*)(lds + (bufoff) + ldsw + _i * 8192), 16, 0, 0); } while (0)
; #define PG8_LDA(dst, b, h) do { _Pragma("unroll") for (int m = 0; m < 4; ++m) _Pragma("unroll") for (int k = 0; k < 2; ++k) dst[m][k] = *(const PG8_LAS bf16x8*)(lds + PG8_SA(b, h) + aoff + m * 2048 + k * 1024); } while (0)
; #define PG8_LDB(dst, b, h) do { _Pragma("unroll") for (int n = 0; n < 2; ++n) _Pragma("unroll") for (int k = 0; k < 2; ++k) dst[n][k] = *(const PG8_LAS bf16x8*)(lds + PG8_SB(b, h) + boff + n * 2048 + k * 1024); } while (0)
; #define PG8_MMA(ai, bj, At, Bt) do { __builtin_amdgcn_s_setprio(1); _Pragma("unroll") for (int m = 0; m < 4; ++m) _Pragma("unroll") for (int n = 0; n < 2; ++n) _Pragma("unroll") for (int k = 0; k < 2; ++k) \
;         acc[ai][bj][m][n] = __builtin_amdgcn_mfma_f32_16x16x32_bf16(Bt[n][k], At[m][k], acc[ai][bj][m][n], 0, 0, 0); __builtin_amdgcn_s_setprio(0); } while (0)
; #define PG8_WAIT_V(n) asm volatile("s_waitcnt vmcnt(" #n ")" ::: "memory")
; #define PG8_WAIT_L(n) asm volatile("s_waitcnt lgkmcnt(" #n ")" ::: "memory")
; #define PG8_BAR __builtin_amdgcn_s_barrier()
; #define PG8_SCHED __builtin_amdgcn_sched_barrier(0)
; template <class Epi, class Sched, bool ALIGN_EPI = false, bool SP2 = false>
; __device__ __forceinline__ void gemm_phase(PG8_LAS unsigned char* lds, const Gemm g, const Sched& S, const Epi& E) {
;     ...
;             const char* a1 = cA + (size_t)(t + 1) * kstep;
;             const char* a2 = last ? nA : cA + (size_t)(t + 2) * kstep; const char* b2 = last ? nB : cB + (size_t)(t + 2) * kstep;
;             const char* a3 = a2 + kstep; const char* b3 = b2 + kstep;
;             if (last && has_next) S.a_ready(nxt);
;             if constexpr (SP2) {
;             PG8_LDB(B0, 0, 0); PG8_LDB(B1, 0, 1); PG8_SCHED; PG8_LDA(At, 0, 0); PG8_STAGE(PG8_SA(1, 1), a1 + hstep, voffA);
;             PG8_WAIT_V(8); PG8_WAIT_L(0); PG8_BAR; PG8_MMA(0, 0, At, B0); PG8_MMA(0, 1, At, B1); PG8_BAR; PG8_SCHED;
;             PG8_LDA(At, 0, 1); PG8_STAGE(PG8_SB(0, 0), b2, voffB); PG8_STAGE(PG8_SB(0, 1), b2 + hstep, voffB); PG8_STAGE(PG8_SA(0, 0), a2, voffA);
.LBB0_507:
	s_add_u32 s28, s26, 0xfffc0080
	s_addc_u32 s29, s27, -1
	s_add_i32 s52, 0, 0x10000
	s_cmp_eq_u32 s68, 12
	s_cselect_b32 s31, s21, s29
	s_cselect_b32 s30, s86, s28
	s_cselect_b32 s29, s19, vcc_hi
	s_cselect_b32 s28, s87, vcc_lo
	s_add_i32 s69, 0, 0x14000
	v_add_u32_e32 v140, s52, v175
	v_add_u32_e32 v162, s69, v175
	ds_read_b128 v[128:131], v140
	ds_read_b128 v[132:135], v140 offset:1024
	ds_read_b128 v[136:139], v140 offset:2048
	ds_read_b128 v[140:143], v140 offset:3072
	ds_read_b128 v[144:147], v162
	ds_read_b128 v[148:151], v162 offset:1024
	ds_read_b128 v[178:181], v162 offset:2048
	ds_read_b128 v[182:185], v162 offset:3072
	v_lshl_add_u64 v[162:163], s[26:27], 0, v[158:159]
	s_add_i32 m0, s41, 0xc000
	ds_read_b128 v[186:189], v233
	ds_read_b128 v[190:193], v233 offset:1024
	ds_read_b128 v[194:197], v233 offset:2048
	ds_read_b128 v[198:201], v233 offset:3072
	ds_read_b128 v[202:205], v233 offset:4096
	ds_read_b128 v[206:209], v233 offset:5120
	ds_read_b128 v[210:213], v233 offset:6144
	ds_read_b128 v[214:217], v233 offset:7168
	global_load_lds_dwordx4 v[162:163], off
	v_lshl_add_u64 v[162:163], s[26:27], 0, v[176:177]
	s_add_i32 m0, s41, 0xe000
	s_nop 0
	global_load_lds_dwordx4 v[162:163], off
	s_waitcnt vmcnt(8)
	s_waitcnt lgkmcnt(0)
	s_barrier
	s_setprio 1
	s_waitcnt lgkmcnt(0)
	v_mfma_f32_16x16x32_bf16 v[124:127], v[128:131], v[186:189], v[124:127]
	v_mfma_f32_16x16x32_bf16 v[120:123], v[136:139], v[186:189], v[120:123]
	v_mfma_f32_16x16x32_bf16 v[108:111], v[128:131], v[194:197], v[108:111]
	v_mfma_f32_16x16x32_bf16 v[104:107], v[136:139], v[194:197], v[104:107]
	v_mfma_f32_16x16x32_bf16 v[92:95], v[128:131], v[202:205], v[92:95]
	v_mfma_f32_16x16x32_bf16 v[88:91], v[136:139], v[202:205], v[88:91]
	v_mfma_f32_16x16x32_bf16 v[76:79], v[128:131], v[210:213], v[76:79]
	v_mfma_f32_16x16x32_bf16 v[72:75], v[136:139], v[210:213], v[72:75]
	v_mfma_f32_16x16x32_bf16 v[124:127], v[132:135], v[190:193], v[124:127]
	v_mfma_f32_16x16x32_bf16 v[120:123], v[140:143], v[190:193], v[120:123]
	v_mfma_f32_16x16x32_bf16 v[108:111], v[132:135], v[198:201], v[108:111]
	v_mfma_f32_16x16x32_bf16 v[104:107], v[140:143], v[198:201], v[104:107]
	v_mfma_f32_16x16x32_bf16 v[92:95], v[132:135], v[206:209], v[92:95]
	v_mfma_f32_16x16x32_bf16 v[88:91], v[140:143], v[206:209], v[88:91]
	v_mfma_f32_16x16x32_bf16 v[76:79], v[132:135], v[214:217], v[76:79]
	v_mfma_f32_16x16x32_bf16 v[72:75], v[140:143], v[214:217], v[72:75]
	v_mfma_f32_16x16x32_bf16 v[116:119], v[144:147], v[186:189], v[116:119]
	v_mfma_f32_16x16x32_bf16 v[112:115], v[178:181], v[186:189], v[112:115]
	v_mfma_f32_16x16x32_bf16 v[100:103], v[144:147], v[194:197], v[100:103]
	v_mfma_f32_16x16x32_bf16 v[96:99], v[178:181], v[194:197], v[96:99]
	v_mfma_f32_16x16x32_bf16 v[84:87], v[144:147], v[202:205], v[84:87]
	v_mfma_f32_16x16x32_bf16 v[80:83], v[178:181], v[202:205], v[80:83]
	v_mfma_f32_16x16x32_bf16 v[68:71], v[144:147], v[210:213], v[68:71]
	v_mfma_f32_16x16x32_bf16 v[64:67], v[178:181], v[210:213], v[64:67]
	v_mfma_f32_16x16x32_bf16 v[116:119], v[148:151], v[190:193], v[116:119]
	v_mfma_f32_16x16x32_bf16 v[112:115], v[182:185], v[190:193], v[112:115]
	v_mfma_f32_16x16x32_bf16 v[100:103], v[148:151], v[198:201], v[100:103]
	v_mfma_f32_16x16x32_bf16 v[96:99], v[182:185], v[198:201], v[96:99]
	v_mfma_f32_16x16x32_bf16 v[84:87], v[148:151], v[206:209], v[84:87]
	v_mfma_f32_16x16x32_bf16 v[80:83], v[182:185], v[206:209], v[80:83]
	v_mfma_f32_16x16x32_bf16 v[68:71], v[148:151], v[214:217], v[68:71]
	v_mfma_f32_16x16x32_bf16 v[64:67], v[182:185], v[214:217], v[64:67]
	s_setprio 0
	s_barrier
	s_add_i32 s52, s52, s40
	v_lshl_add_u64 v[162:163], s[28:29], 0, v[160:161]
	s_mov_b32 m0, s52
	ds_read_b128 v[186:189], v233 offset:16384
	ds_read_b128 v[190:193], v233 offset:17408
	ds_read_b128 v[194:197], v233 offset:18432
	ds_read_b128 v[198:201], v233 offset:19456
	ds_read_b128 v[202:205], v233 offset:20480
	ds_read_b128 v[206:209], v233 offset:21504
	ds_read_b128 v[210:213], v233 offset:22528
	ds_read_b128 v[214:217], v233 offset:23552
	global_load_lds_dwordx4 v[162:163], off
	s_add_i32 m0, s52, 0x2000
	s_add_u32 s52, s28, 0x40000
	v_lshl_add_u64 v[164:165], s[28:29], 0, v[152:153]
	s_addc_u32 s53, s29, 0
	s_add_i32 s69, s69, s40
	global_load_lds_dwordx4 v[164:165], off
	v_lshl_add_u64 v[218:219], s[52:53], 0, v[160:161]
	s_mov_b32 m0, s69
	v_lshl_add_u64 v[220:221], s[30:31], 0, v[154:155]
	global_load_lds_dwordx4 v[218:219], off
	v_lshl_add_u64 v[218:219], s[52:53], 0, v[152:153]
	s_add_i32 m0, s69, 0x2000
	s_nop 0
	global_load_lds_dwordx4 v[218:219], off
	v_lshl_add_u64 v[218:219], s[30:31], 0, v[156:157]
	s_mov_b32 m0, s41
	s_nop 0
	global_load_lds_dwordx4 v[218:219], off
	s_mov_b32 m0, s42
	s_nop 0
	global_load_lds_dwordx4 v[220:221], off
	s_waitcnt vmcnt(8)
	s_waitcnt lgkmcnt(0)
	s_barrier
; #define PG8_STAGE(bufoff, gbase, voff) do { _Pragma("unroll") for (int _i = 0; _i < 2; ++_i) \
;         __builtin_amdgcn_global_load_lds((const unsigned*)((const char*)(gbase) + (voff)[_i]), (PG8_LAS unsigned*)(lds + (bufoff) + ldsw + _i * 8192), 16, 0, 0); } while (0)
; #define PG8_LDA(dst, b, h) do { _Pragma("unroll") for (int m = 0; m < 4; ++m) _Pragma("unroll") for (int k = 0; k < 2; ++k) dst[m][k] = *(const PG8_LAS bf16x8*)(lds + PG8_SA(b, h) + aoff + m * 2048 + k * 1024); } while (0)
; #define PG8_LDB(dst, b, h) do { _Pragma("unroll") for (int n = 0; n < 2; ++n) _Pragma("unroll") for (int k = 0; k < 2; ++k) dst[n][k] = *(const PG8_LAS bf16x8*)(lds + PG8_SB(b, h) + boff + n * 2048 + k * 1024); } while (0)
; #define PG8_MMA(ai, bj, At, Bt) do { __builtin_amdgcn_s_setprio(1); _Pragma("unroll") for (int m = 0; m < 4; ++m) _Pragma("unroll") for (int n = 0; n < 2; ++n) _Pragma("unroll") for (int k = 0; k < 2; ++k) \
;         acc[ai][bj][m][n] = __builtin_amdgcn_mfma_f32_16x16x32_bf16(Bt[n][k], At[m][k], acc[ai][bj][m][n], 0, 0, 0); __builtin_amdgcn_s_setprio(0); } while (0)
; #define PG8_WAIT_V(n) asm volatile("s_waitcnt vmcnt(" #n ")" ::: "memory")
; #define PG8_WAIT_L(n) asm volatile("s_waitcnt lgkmcnt(" #n ")" ::: "memory")
; #define PG8_BAR __builtin_amdgcn_s_barrier()
; #define PG8_SCHED __builtin_amdgcn_sched_barrier(0)
; template <class Epi, class Sched, bool ALIGN_EPI = false, bool SP2 = false>
; __device__ __forceinline__ void gemm_phase(PG8_LAS unsigned char* lds, const Gemm g, const Sched& S, const Epi& E) {
;     ...
;             PG8_WAIT_V(8); PG8_WAIT_L(0); PG8_BAR; PG8_MMA(1, 0, At, B0); PG8_MMA(1, 1, At, B1); PG8_BAR; PG8_SCHED;
;             PG8_LDB(B0, 1, 0); PG8_LDB(B1, 1, 1); PG8_SCHED; PG8_LDA(At, 1, 0); PG8_STAGE(PG8_SA(0, 1), a2 + hstep, voffA);
;             PG8_WAIT_V(8); PG8_WAIT_L(0); PG8_BAR; PG8_MMA(0, 0, At, B0); PG8_MMA(0, 1, At, B1); PG8_BAR; PG8_SCHED;
	s_setprio 1
	s_waitcnt lgkmcnt(0)
	v_mfma_f32_16x16x32_bf16 v[60:63], v[128:131], v[186:189], v[60:63]
	v_mfma_f32_16x16x32_bf16 v[56:59], v[136:139], v[186:189], v[56:59]
	v_mfma_f32_16x16x32_bf16 v[44:47], v[128:131], v[194:197], v[44:47]
	v_mfma_f32_16x16x32_bf16 v[40:43], v[136:139], v[194:197], v[40:43]
	v_mfma_f32_16x16x32_bf16 v[28:31], v[128:131], v[202:205], v[28:31]
	v_mfma_f32_16x16x32_bf16 v[24:27], v[136:139], v[202:205], v[24:27]
	v_mfma_f32_16x16x32_bf16 v[12:15], v[128:131], v[210:213], v[12:15]
	v_mfma_f32_16x16x32_bf16 v[8:11], v[136:139], v[210:213], v[8:11]
	v_mfma_f32_16x16x32_bf16 v[60:63], v[132:135], v[190:193], v[60:63]
	v_mfma_f32_16x16x32_bf16 v[56:59], v[140:143], v[190:193], v[56:59]
	v_mfma_f32_16x16x32_bf16 v[44:47], v[132:135], v[198:201], v[44:47]
	v_mfma_f32_16x16x32_bf16 v[40:43], v[140:143], v[198:201], v[40:43]
	v_mfma_f32_16x16x32_bf16 v[28:31], v[132:135], v[206:209], v[28:31]
	v_mfma_f32_16x16x32_bf16 v[24:27], v[140:143], v[206:209], v[24:27]
	v_mfma_f32_16x16x32_bf16 v[12:15], v[132:135], v[214:217], v[12:15]
	v_mfma_f32_16x16x32_bf16 v[8:11], v[140:143], v[214:217], v[8:11]
	v_mfma_f32_16x16x32_bf16 v[52:55], v[144:147], v[186:189], v[52:55]
	v_mfma_f32_16x16x32_bf16 v[48:51], v[178:181], v[186:189], v[48:51]
	v_mfma_f32_16x16x32_bf16 v[36:39], v[144:147], v[194:197], v[36:39]
	v_mfma_f32_16x16x32_bf16 v[32:35], v[178:181], v[194:197], v[32:35]
	v_mfma_f32_16x16x32_bf16 v[20:23], v[144:147], v[202:205], v[20:23]
	v_mfma_f32_16x16x32_bf16 v[16:19], v[178:181], v[202:205], v[16:19]
	v_mfma_f32_16x16x32_bf16 v[4:7], v[144:147], v[210:213], v[4:7]
	v_mfma_f32_16x16x32_bf16 v[0:3], v[178:181], v[210:213], v[0:3]
	v_mfma_f32_16x16x32_bf16 v[52:55], v[148:151], v[190:193], v[52:55]
	v_mfma_f32_16x16x32_bf16 v[48:51], v[182:185], v[190:193], v[48:51]
	v_mfma_f32_16x16x32_bf16 v[36:39], v[148:151], v[198:201], v[36:39]
	v_mfma_f32_16x16x32_bf16 v[32:35], v[182:185], v[198:201], v[32:35]
	v_mfma_f32_16x16x32_bf16 v[20:23], v[148:151], v[206:209], v[20:23]
	v_mfma_f32_16x16x32_bf16 v[16:19], v[182:185], v[206:209], v[16:19]
	v_mfma_f32_16x16x32_bf16 v[4:7], v[148:151], v[214:217], v[4:7]
	v_mfma_f32_16x16x32_bf16 v[0:3], v[182:185], v[214:217], v[0:3]
	s_setprio 0
	s_barrier
	s_add_i32 s52, 0, 0x18000
	s_add_i32 s53, 0, 0x1c000
	v_add_u32_e32 v140, s52, v175
	v_add_u32_e32 v182, s53, v175
	ds_read_b128 v[128:131], v140
	ds_read_b128 v[132:135], v140 offset:1024
	ds_read_b128 v[136:139], v140 offset:2048
	ds_read_b128 v[140:143], v140 offset:3072
	ds_read_b128 v[144:147], v182
	ds_read_b128 v[148:151], v182 offset:1024
	ds_read_b128 v[178:181], v182 offset:2048
	ds_read_b128 v[182:185], v182 offset:3072
	s_add_u32 s30, s30, 0x40000
	s_addc_u32 s31, s31, 0
	s_mov_b32 m0, s43
	v_lshl_add_u64 v[222:223], s[30:31], 0, v[156:157]
	ds_read_b128 v[186:189], v233 offset:32768
	ds_read_b128 v[190:193], v233 offset:33792
	ds_read_b128 v[194:197], v233 offset:34816
	ds_read_b128 v[198:201], v233 offset:35840
	ds_read_b128 v[202:205], v233 offset:36864
	ds_read_b128 v[206:209], v233 offset:37888
	ds_read_b128 v[210:213], v233 offset:38912
	ds_read_b128 v[214:217], v233 offset:39936
	global_load_lds_dwordx4 v[222:223], off
	v_lshl_add_u64 v[222:223], s[30:31], 0, v[154:155]
	s_mov_b32 m0, s44
	s_nop 0
	global_load_lds_dwordx4 v[222:223], off
	s_waitcnt vmcnt(8)
	s_waitcnt lgkmcnt(0)
	s_barrier
	s_setprio 1
	s_waitcnt lgkmcnt(0)
	v_mfma_f32_16x16x32_bf16 v[124:127], v[128:131], v[186:189], v[124:127]
	v_mfma_f32_16x16x32_bf16 v[120:123], v[136:139], v[186:189], v[120:123]
	v_mfma_f32_16x16x32_bf16 v[108:111], v[128:131], v[194:197], v[108:111]
	v_mfma_f32_16x16x32_bf16 v[104:107], v[136:139], v[194:197], v[104:107]
	v_mfma_f32_16x16x32_bf16 v[92:95], v[128:131], v[202:205], v[92:95]
	v_mfma_f32_16x16x32_bf16 v[88:91], v[136:139], v[202:205], v[88:91]
	v_mfma_f32_16x16x32_bf16 v[76:79], v[128:131], v[210:213], v[76:79]
	v_mfma_f32_16x16x32_bf16 v[72:75], v[136:139], v[210:213], v[72:75]
	v_mfma_f32_16x16x32_bf16 v[124:127], v[132:135], v[190:193], v[124:127]
	v_mfma_f32_16x16x32_bf16 v[120:123], v[140:143], v[190:193], v[120:123]
	v_mfma_f32_16x16x32_bf16 v[108:111], v[132:135], v[198:201], v[108:111]
	v_mfma_f32_16x16x32_bf16 v[104:107], v[140:143], v[198:201], v[104:107]
	v_mfma_f32_16x16x32_bf16 v[92:95], v[132:135], v[206:209], v[92:95]
	v_mfma_f32_16x16x32_bf16 v[88:91], v[140:143], v[206:209], v[88:91]
	v_mfma_f32_16x16x32_bf16 v[76:79], v[132:135], v[214:217], v[76:79]
	v_mfma_f32_16x16x32_bf16 v[72:75], v[140:143], v[214:217], v[72:75]
	v_mfma_f32_16x16x32_bf16 v[116:119], v[144:147], v[186:189], v[116:119]
	v_mfma_f32_16x16x32_bf16 v[112:115], v[178:181], v[186:189], v[112:115]
	v_mfma_f32_16x16x32_bf16 v[100:103], v[144:147], v[194:197], v[100:103]
	v_mfma_f32_16x16x32_bf16 v[96:99], v[178:181], v[194:197], v[96:99]
	v_mfma_f32_16x16x32_bf16 v[84:87], v[144:147], v[202:205], v[84:87]
	v_mfma_f32_16x16x32_bf16 v[80:83], v[178:181], v[202:205], v[80:83]
	v_mfma_f32_16x16x32_bf16 v[68:71], v[144:147], v[210:213], v[68:71]
	v_mfma_f32_16x16x32_bf16 v[64:67], v[178:181], v[210:213], v[64:67]
	v_mfma_f32_16x16x32_bf16 v[116:119], v[148:151], v[190:193], v[116:119]
	v_mfma_f32_16x16x32_bf16 v[112:115], v[182:185], v[190:193], v[112:115]
	v_mfma_f32_16x16x32_bf16 v[100:103], v[148:151], v[198:201], v[100:103]
	v_mfma_f32_16x16x32_bf16 v[96:99], v[182:185], v[198:201], v[96:99]
	v_mfma_f32_16x16x32_bf16 v[84:87], v[148:151], v[206:209], v[84:87]
	v_mfma_f32_16x16x32_bf16 v[80:83], v[182:185], v[206:209], v[80:83]
	v_mfma_f32_16x16x32_bf16 v[68:71], v[148:151], v[214:217], v[68:71]
	v_mfma_f32_16x16x32_bf16 v[64:67], v[182:185], v[214:217], v[64:67]
	s_setprio 0
	s_barrier
; #define PG8_STAGE(bufoff, gbase, voff) do { _Pragma("unroll") for (int _i = 0; _i < 2; ++_i) \
;         __builtin_amdgcn_global_load_lds((const unsigned*)((const char*)(gbase) + (voff)[_i]), (PG8_LAS unsigned*)(lds + (bufoff) + ldsw + _i * 8192), 16, 0, 0); } while (0)
; #define PG8_LDA(dst, b, h) do { _Pragma("unroll") for (int m = 0; m < 4; ++m) _Pragma("unroll") for (int k = 0; k < 2; ++k) dst[m][k] = *(const PG8_LAS bf16x8*)(lds + PG8_SA(b, h) + aoff + m * 2048 + k * 1024); } while (0)
; #define PG8_MMA(ai, bj, At, Bt) do { __builtin_amdgcn_s_setprio(1); _Pragma("unroll") for (int m = 0; m < 4; ++m) _Pragma("unroll") for (int n = 0; n < 2; ++n) _Pragma("unroll") for (int k = 0; k < 2; ++k) \
;         acc[ai][bj][m][n] = __builtin_amdgcn_mfma_f32_16x16x32_bf16(Bt[n][k], At[m][k], acc[ai][bj][m][n], 0, 0, 0); __builtin_amdgcn_s_setprio(0); } while (0)
; #define PG8_WAIT_V(n) asm volatile("s_waitcnt vmcnt(" #n ")" ::: "memory")
; #define PG8_WAIT_L(n) asm volatile("s_waitcnt lgkmcnt(" #n ")" ::: "memory")
; #define PG8_BAR __builtin_amdgcn_s_barrier()
; #define PG8_SCHED __builtin_amdgcn_sched_barrier(0)
; template <class Epi, class Sched, bool ALIGN_EPI = false, bool SP2 = false>
; __device__ __forceinline__ void gemm_phase(PG8_LAS unsigned char* lds, const Gemm g, const Sched& S, const Epi& E) {
;     ...
;             PG8_LDA(At, 1, 1); PG8_STAGE(PG8_SB(1, 0), b3, voffB); PG8_STAGE(PG8_SB(1, 1), b3 + hstep, voffB); PG8_STAGE(PG8_SA(1, 0), a3, voffA);
;             PG8_WAIT_V(8); PG8_WAIT_L(0); PG8_BAR; PG8_MMA(1, 0, At, B0); PG8_MMA(1, 1, At, B1); PG8_BAR; PG8_SCHED;
;     ...
;         if constexpr (ALIGN_EPI) { if (wr == 0) PG8_BAR; }
	s_add_i32 s30, s52, s40
	v_lshl_add_u64 v[162:163], v[162:163], 0, s[50:51]
	s_mov_b32 m0, s30
	ds_read_b128 v[186:189], v233 offset:49152
	ds_read_b128 v[190:193], v233 offset:50176
	ds_read_b128 v[194:197], v233 offset:51200
	ds_read_b128 v[198:201], v233 offset:52224
	ds_read_b128 v[202:205], v233 offset:53248
	ds_read_b128 v[206:209], v233 offset:54272
	ds_read_b128 v[210:213], v233 offset:55296
	ds_read_b128 v[214:217], v233 offset:56320
	global_load_lds_dwordx4 v[162:163], off
	s_add_i32 m0, s30, 0x2000
	s_add_u32 s28, s28, 0x40080
	v_lshl_add_u64 v[162:163], v[164:165], 0, s[50:51]
	s_addc_u32 s29, s29, 0
	s_add_i32 s30, s53, s40
	global_load_lds_dwordx4 v[162:163], off
	v_lshl_add_u64 v[162:163], s[28:29], 0, v[160:161]
	s_mov_b32 m0, s30
	s_nop 0
	global_load_lds_dwordx4 v[162:163], off
	v_lshl_add_u64 v[162:163], s[28:29], 0, v[152:153]
	s_add_i32 m0, s30, 0x2000
	s_nop 0
	global_load_lds_dwordx4 v[162:163], off
	v_lshl_add_u64 v[162:163], v[218:219], 0, s[50:51]
	s_mov_b32 m0, s46
	s_nop 0
	global_load_lds_dwordx4 v[162:163], off
	v_lshl_add_u64 v[162:163], v[220:221], 0, s[50:51]
	s_mov_b32 m0, s47
	s_nop 0
	global_load_lds_dwordx4 v[162:163], off
	s_waitcnt vmcnt(8)
	s_waitcnt lgkmcnt(0)
	s_barrier
	s_setprio 1
	s_waitcnt lgkmcnt(0)
	v_mfma_f32_16x16x32_bf16 v[60:63], v[128:131], v[186:189], v[60:63]
	v_mfma_f32_16x16x32_bf16 v[56:59], v[136:139], v[186:189], v[56:59]
	v_mfma_f32_16x16x32_bf16 v[44:47], v[128:131], v[194:197], v[44:47]
	v_mfma_f32_16x16x32_bf16 v[40:43], v[136:139], v[194:197], v[40:43]
	v_mfma_f32_16x16x32_bf16 v[28:31], v[128:131], v[202:205], v[28:31]
	v_mfma_f32_16x16x32_bf16 v[24:27], v[136:139], v[202:205], v[24:27]
	v_mfma_f32_16x16x32_bf16 v[12:15], v[128:131], v[210:213], v[12:15]
	v_mfma_f32_16x16x32_bf16 v[8:11], v[136:139], v[210:213], v[8:11]
	v_mfma_f32_16x16x32_bf16 v[60:63], v[132:135], v[190:193], v[60:63]
	v_mfma_f32_16x16x32_bf16 v[56:59], v[140:143], v[190:193], v[56:59]
	v_mfma_f32_16x16x32_bf16 v[44:47], v[132:135], v[198:201], v[44:47]
	v_mfma_f32_16x16x32_bf16 v[40:43], v[140:143], v[198:201], v[40:43]
	v_mfma_f32_16x16x32_bf16 v[28:31], v[132:135], v[206:209], v[28:31]
	v_mfma_f32_16x16x32_bf16 v[24:27], v[140:143], v[206:209], v[24:27]
	v_mfma_f32_16x16x32_bf16 v[12:15], v[132:135], v[214:217], v[12:15]
	v_mfma_f32_16x16x32_bf16 v[8:11], v[140:143], v[214:217], v[8:11]
	v_mfma_f32_16x16x32_bf16 v[52:55], v[144:147], v[186:189], v[52:55]
	v_mfma_f32_16x16x32_bf16 v[48:51], v[178:181], v[186:189], v[48:51]
	v_mfma_f32_16x16x32_bf16 v[36:39], v[144:147], v[194:197], v[36:39]
	v_mfma_f32_16x16x32_bf16 v[32:35], v[178:181], v[194:197], v[32:35]
	v_mfma_f32_16x16x32_bf16 v[20:23], v[144:147], v[202:205], v[20:23]
	v_mfma_f32_16x16x32_bf16 v[16:19], v[178:181], v[202:205], v[16:19]
	v_mfma_f32_16x16x32_bf16 v[4:7], v[144:147], v[210:213], v[4:7]
	v_mfma_f32_16x16x32_bf16 v[0:3], v[178:181], v[210:213], v[0:3]
	v_mfma_f32_16x16x32_bf16 v[52:55], v[148:151], v[190:193], v[52:55]
	v_mfma_f32_16x16x32_bf16 v[48:51], v[182:185], v[190:193], v[48:51]
	v_mfma_f32_16x16x32_bf16 v[36:39], v[148:151], v[198:201], v[36:39]
	v_mfma_f32_16x16x32_bf16 v[32:35], v[182:185], v[198:201], v[32:35]
	v_mfma_f32_16x16x32_bf16 v[20:23], v[148:151], v[206:209], v[20:23]
	v_mfma_f32_16x16x32_bf16 v[16:19], v[182:185], v[206:209], v[16:19]
	v_mfma_f32_16x16x32_bf16 v[4:7], v[148:151], v[214:217], v[4:7]
	v_mfma_f32_16x16x32_bf16 v[0:3], v[182:185], v[214:217], v[0:3]
	s_setprio 0
	s_barrier
	s_add_i32 s68, s68, 2
	s_add_u32 s26, s26, 0x100
	s_addc_u32 s27, s27, 0
	s_add_u32 vcc_lo, vcc_lo, 0x100
	s_addc_u32 vcc_hi, vcc_hi, 0
	s_cmp_gt_u32 s68, 13
	s_cbranch_scc0 .LBB0_507
	s_and_b64 vcc, exec, s[16:17]
	s_cbranch_vccz .LBB0_510
	s_barrier
